# S5 pass 1/2 recurrences: the per-step LDS reads of B*u are hoisted to the start of each 16-step block (groups of 8, counted lgkmcnt) instead of one exposed LDS round trip per step
# speedup vs baseline: 1.0041x; 1.0041x over previous
; __device__ __forceinline__ void s5_bu16(const S5Frag& f, const bf16x8 uf, float* buL, int lane) {
;     const int jj = lane & 15, quad = lane >> 4;
; #pragma unroll
;     for (int nt = 0; nt < 4; ++nt) {
;         const f32x4 z = (f32x4){0.f, 0.f, 0.f, 0.f};
;         const f32x4 dre = __builtin_amdgcn_mfma_f32_16x16x32_bf16(uf, f.bfr[nt], z, 0, 0, 0);
;         const f32x4 dim = __builtin_amdgcn_mfma_f32_16x16x32_bf16(uf, f.bfr[nt + 4], z, 0, 0, 0);
; #pragma unroll
;         for (int r = 0; r < 4; ++r) *(f32x2*)(buL + ((4 * quad + r) * 64 + 16 * nt + jj) * 2) = (f32x2){dre[r], dim[r]};
;     }
; __device__ __forceinline__ void s5_pass1_item(PP p, unsigned char* shm, int item, int l) {
;     ...
;     for (int sc = 0; sc < 4; ++sc) {
;         s5_bu16(f, uf[sc], buL, lane);
;         __syncthreads();
; #pragma unroll
;         for (int t = 0; t < 16; ++t) s5_rec(q, *(const f32x2*)(buL + (t * 64 + lane) * 2), x);
.LBB0_552:
	s_or_b64 exec, exec, s[2:3]
	v_mul_f32_e32 v50, v59, v57
	v_lshl_add_u32 v52, v56, 13, 0
	s_waitcnt lgkmcnt(1)
	v_mfma_f32_16x16x32_bf16 v[56:59], v[46:49], v[26:29], 0
	v_and_b32_e32 v0, 0x600, v51
	v_lshl_add_u32 v51, v0, 2, v52
	v_lshlrev_b32_e32 v0, 3, v55
	v_mfma_f32_16x16x32_bf16 v[60:63], v[46:49], v[38:41], 0
	v_and_b32_e32 v55, 0x78, v0
	s_nop 2
	v_mov_b32_e32 v68, v56
	v_mov_b32_e32 v70, v58
	s_waitcnt lgkmcnt(0)
	v_mfma_f32_16x16x32_bf16 v[64:67], v[46:49], v[34:37], 0
	v_add_u32_e32 v74, v51, v55
	v_mov_b32_e32 v69, v60
	v_mov_b32_e32 v60, v57
	v_mov_b32_e32 v71, v62
	v_mov_b32_e32 v62, v59
	v_mfma_f32_16x16x32_bf16 v[56:59], v[46:49], v[14:17], 0
	v_or_b32_e32 v55, 0x180, v0
	v_add_u32_e32 v55, v51, v55
	v_add_u32_e32 v51, v52, v0
	v_mov_b32_e32 v52, v53
	v_mov_b32_e32 v73, v64
	s_nop 2
	v_mov_b32_e32 v72, v56
	v_add_u32_e32 v53, 0x1000, v74
	v_mov_b32_e32 v64, v57
	v_mov_b32_e32 v56, v58
	v_mov_b32_e32 v57, v66
	ds_write2_b64 v53, v[68:69], v[72:73] offset1:16
	ds_write2_b64 v53, v[70:71], v[56:57] offset0:128 offset1:144
	v_mov_b32_e32 v66, v59
	v_mfma_f32_16x16x32_bf16 v[56:59], v[46:49], v[6:9], 0
	v_readlane_b32 s2, v255, 9
	v_readlane_b32 s3, v255, 10
	s_mov_b32 s3, s19
	v_mfma_f32_16x16x32_bf16 v[68:71], v[46:49], v[18:21], 0
	s_mov_b32 s18, s2
	s_nop 2
	v_mov_b32_e32 v72, v56
	v_mov_b32_e32 v56, v58
	v_writelane_b32 v255, s18, 9
	s_nop 1
	v_writelane_b32 v255, s19, 10
	v_mov_b32_e32 v73, v68
	v_mov_b32_e32 v68, v57
	v_mov_b32_e32 v57, v70
	ds_write2_b64 v53, v[56:57], v[62:63] offset0:160 offset1:192
	v_mov_b32_e32 v70, v59
	v_mfma_f32_16x16x32_bf16 v[56:59], v[46:49], v[10:13], 0
	ds_write2_b64 v53, v[72:73], v[60:61] offset0:32 offset1:64
	ds_write2_b64 v53, v[64:65], v[68:69] offset0:80 offset1:96
	ds_write2_b64 v53, v[66:67], v[70:71] offset0:208 offset1:224
	v_mfma_f32_16x16x32_bf16 v[46:49], v[46:49], v[22:25], 0
	s_nop 3
	v_mov_b32_e32 v60, v56
	s_nop 2
	v_mov_b32_e32 v61, v46
	v_mov_b32_e32 v46, v57
	ds_write2st64_b64 v55, v[60:61], v[46:47] offset0:8 offset1:9
	v_mov_b32_e32 v46, v58
	v_mov_b32_e32 v47, v48
	v_mov_b32_e32 v48, v59
	ds_write2st64_b64 v55, v[46:47], v[48:49] offset0:10 offset1:11
	s_waitcnt lgkmcnt(0)
	s_barrier
	ds_read2st64_b64 v[180:183], v51 offset0:8 offset1:9
	ds_read2st64_b64 v[184:187], v51 offset0:10 offset1:11
	ds_read2st64_b64 v[188:191], v51 offset0:12 offset1:13
	ds_read2st64_b64 v[192:195], v51 offset0:14 offset1:15
	ds_read2st64_b64 v[196:199], v51 offset0:16 offset1:17
	ds_read2st64_b64 v[200:203], v51 offset0:18 offset1:19
	ds_read2st64_b64 v[204:207], v51 offset0:20 offset1:21
	ds_read2st64_b64 v[208:211], v51 offset0:22 offset1:23
	v_pk_mul_f32 v[56:57], v[52:53], s[2:3] op_sel_hi:[0,1]
	v_pk_fma_f32 v[56:57], v[50:51], 0, v[56:57] op_sel_hi:[0,0,1]
	v_mfma_f32_16x16x32_bf16 v[60:63], v[42:45], v[34:37], 0
	s_lshl_b32 s2, s34, 10
	s_waitcnt lgkmcnt(7)
	v_pk_add_f32 v[46:47], v[56:57], v[180:181]
	s_lshl_b32 s3, s9, 5
	v_xor_b32_e32 v56, 0x80000000, v47
	v_mov_b32_e32 v57, v46
	v_pk_mul_f32 v[56:57], v[52:53], v[56:57] op_sel_hi:[0,1]
	v_pk_fma_f32 v[46:47], v[50:51], v[46:47], v[56:57] op_sel_hi:[0,1,1]
	v_pk_add_f32 v[56:57], v[182:183], v[46:47]
	v_xor_b32_e32 v58, 0x80000000, v57
	v_mov_b32_e32 v59, v56
	v_pk_mul_f32 v[58:59], v[52:53], v[58:59] op_sel_hi:[0,1]
	v_pk_fma_f32 v[56:57], v[50:51], v[56:57], v[58:59] op_sel_hi:[0,1,1]
	s_waitcnt lgkmcnt(6)
	v_pk_add_f32 v[46:47], v[184:185], v[56:57]
	v_mov_b32_e32 v71, v60
	v_xor_b32_e32 v56, 0x80000000, v47
	v_mov_b32_e32 v57, v46
	v_pk_mul_f32 v[56:57], v[52:53], v[56:57] op_sel_hi:[0,1]
	v_pk_fma_f32 v[46:47], v[50:51], v[46:47], v[56:57] op_sel_hi:[0,1,1]
	v_pk_add_f32 v[56:57], v[186:187], v[46:47]
	v_xor_b32_e32 v58, 0x80000000, v57
	v_mov_b32_e32 v59, v56
	v_pk_mul_f32 v[58:59], v[52:53], v[58:59] op_sel_hi:[0,1]
	v_pk_fma_f32 v[56:57], v[50:51], v[56:57], v[58:59] op_sel_hi:[0,1,1]
	s_waitcnt lgkmcnt(5)
	v_pk_add_f32 v[46:47], v[188:189], v[56:57]
	s_add_i32 s3, s3, s2
	v_xor_b32_e32 v56, 0x80000000, v47
	v_mov_b32_e32 v57, v46
	v_pk_mul_f32 v[56:57], v[52:53], v[56:57] op_sel_hi:[0,1]
	v_pk_fma_f32 v[46:47], v[50:51], v[46:47], v[56:57] op_sel_hi:[0,1,1]
	v_pk_add_f32 v[56:57], v[190:191], v[46:47]
	v_xor_b32_e32 v58, 0x80000000, v57
	v_mov_b32_e32 v59, v56
	v_pk_mul_f32 v[58:59], v[52:53], v[58:59] op_sel_hi:[0,1]
	v_pk_fma_f32 v[56:57], v[50:51], v[56:57], v[58:59] op_sel_hi:[0,1,1]
	s_waitcnt lgkmcnt(4)
	v_pk_add_f32 v[46:47], v[192:193], v[56:57]
	s_nop 0
	v_xor_b32_e32 v56, 0x80000000, v47
	v_mov_b32_e32 v57, v46
	v_pk_mul_f32 v[56:57], v[52:53], v[56:57] op_sel_hi:[0,1]
	v_pk_fma_f32 v[46:47], v[50:51], v[46:47], v[56:57] op_sel_hi:[0,1,1]
	v_pk_add_f32 v[56:57], v[194:195], v[46:47]
	v_xor_b32_e32 v58, 0x80000000, v57
	v_mov_b32_e32 v59, v56
	v_pk_mul_f32 v[58:59], v[52:53], v[58:59] op_sel_hi:[0,1]
	v_pk_fma_f32 v[56:57], v[50:51], v[56:57], v[58:59] op_sel_hi:[0,1,1]
	s_waitcnt lgkmcnt(3)
	v_pk_add_f32 v[46:47], v[196:197], v[56:57]
	s_nop 0
	v_xor_b32_e32 v56, 0x80000000, v47
	v_mov_b32_e32 v57, v46
	v_pk_mul_f32 v[56:57], v[52:53], v[56:57] op_sel_hi:[0,1]
	v_pk_fma_f32 v[46:47], v[50:51], v[46:47], v[56:57] op_sel_hi:[0,1,1]
	v_pk_add_f32 v[56:57], v[198:199], v[46:47]
	v_xor_b32_e32 v58, 0x80000000, v57
	v_mov_b32_e32 v59, v56
	v_pk_mul_f32 v[58:59], v[52:53], v[58:59] op_sel_hi:[0,1]
	v_pk_fma_f32 v[56:57], v[50:51], v[56:57], v[58:59] op_sel_hi:[0,1,1]
	s_waitcnt lgkmcnt(2)
	v_pk_add_f32 v[46:47], v[200:201], v[56:57]
	s_nop 0
	v_xor_b32_e32 v56, 0x80000000, v47
	v_mov_b32_e32 v57, v46
	v_pk_mul_f32 v[56:57], v[52:53], v[56:57] op_sel_hi:[0,1]
	v_pk_fma_f32 v[46:47], v[50:51], v[46:47], v[56:57] op_sel_hi:[0,1,1]
	v_pk_add_f32 v[56:57], v[202:203], v[46:47]
	v_xor_b32_e32 v58, 0x80000000, v57
	v_mov_b32_e32 v59, v56
	v_pk_mul_f32 v[58:59], v[52:53], v[58:59] op_sel_hi:[0,1]
	v_pk_fma_f32 v[56:57], v[50:51], v[56:57], v[58:59] op_sel_hi:[0,1,1]
	s_waitcnt lgkmcnt(1)
	v_pk_add_f32 v[46:47], v[204:205], v[56:57]
	s_nop 0
	v_xor_b32_e32 v56, 0x80000000, v47
	v_mov_b32_e32 v57, v46
	v_pk_mul_f32 v[56:57], v[52:53], v[56:57] op_sel_hi:[0,1]
	v_pk_fma_f32 v[46:47], v[50:51], v[46:47], v[56:57] op_sel_hi:[0,1,1]
	v_pk_add_f32 v[56:57], v[206:207], v[46:47]
	v_xor_b32_e32 v58, 0x80000000, v57
	v_mov_b32_e32 v59, v56
	v_pk_mul_f32 v[58:59], v[52:53], v[58:59] op_sel_hi:[0,1]
	v_pk_fma_f32 v[56:57], v[50:51], v[56:57], v[58:59] op_sel_hi:[0,1,1]
	s_waitcnt lgkmcnt(0)
	v_pk_add_f32 v[46:47], v[208:209], v[56:57]
	s_nop 0
	v_xor_b32_e32 v56, 0x80000000, v47
	v_mov_b32_e32 v57, v46
	v_pk_mul_f32 v[56:57], v[52:53], v[56:57] op_sel_hi:[0,1]
	v_pk_fma_f32 v[46:47], v[50:51], v[46:47], v[56:57] op_sel_hi:[0,1,1]
	v_pk_add_f32 v[68:69], v[210:211], v[46:47]
	v_mfma_f32_16x16x32_bf16 v[46:49], v[42:45], v[26:29], 0
	s_barrier
; __device__ __forceinline__ void s5_bu16(const S5Frag& f, const bf16x8 uf, float* buL, int lane) {
;     const int jj = lane & 15, quad = lane >> 4;
; #pragma unroll
;     for (int nt = 0; nt < 4; ++nt) {
;         const f32x4 z = (f32x4){0.f, 0.f, 0.f, 0.f};
;         const f32x4 dre = __builtin_amdgcn_mfma_f32_16x16x32_bf16(uf, f.bfr[nt], z, 0, 0, 0);
;         const f32x4 dim = __builtin_amdgcn_mfma_f32_16x16x32_bf16(uf, f.bfr[nt + 4], z, 0, 0, 0);
; #pragma unroll
;         for (int r = 0; r < 4; ++r) *(f32x2*)(buL + ((4 * quad + r) * 64 + 16 * nt + jj) * 2) = (f32x2){dre[r], dim[r]};
;     }
; __device__ __forceinline__ void s5_pass1_item(PP p, unsigned char* shm, int item, int l) {
;     ...
;     for (int sc = 0; sc < 4; ++sc) {
;         s5_bu16(f, uf[sc], buL, lane);
;         __syncthreads();
; #pragma unroll
;         for (int t = 0; t < 16; ++t) s5_rec(q, *(const f32x2*)(buL + (t * 64 + lane) * 2), x);
	v_mfma_f32_16x16x32_bf16 v[56:59], v[42:45], v[38:41], 0
	s_nop 5
	v_mov_b32_e32 v64, v46
	s_nop 0
	v_mov_b32_e32 v65, v56
	v_mov_b32_e32 v56, v47
	v_mov_b32_e32 v66, v48
	v_mov_b32_e32 v67, v58
	v_mov_b32_e32 v58, v49
	v_mfma_f32_16x16x32_bf16 v[46:49], v[42:45], v[14:17], 0
	s_nop 7
	v_mov_b32_e32 v70, v46
	v_mov_b32_e32 v60, v47
	v_mov_b32_e32 v46, v48
	v_mov_b32_e32 v47, v62
	ds_write2_b64 v53, v[64:65], v[70:71] offset1:16
	ds_write2_b64 v53, v[66:67], v[46:47] offset0:128 offset1:144
	v_mov_b32_e32 v62, v49
	v_mfma_f32_16x16x32_bf16 v[46:49], v[42:45], v[6:9], 0
	v_mfma_f32_16x16x32_bf16 v[64:67], v[42:45], v[18:21], 0
	s_nop 6
	v_mov_b32_e32 v70, v46
	v_mov_b32_e32 v71, v64
	v_mov_b32_e32 v64, v47
	v_mov_b32_e32 v46, v48
	v_mov_b32_e32 v47, v66
	ds_write2_b64 v53, v[46:47], v[58:59] offset0:160 offset1:192
	v_mov_b32_e32 v66, v49
	v_mfma_f32_16x16x32_bf16 v[46:49], v[42:45], v[10:13], 0
	ds_write2_b64 v53, v[70:71], v[56:57] offset0:32 offset1:64
	ds_write2_b64 v53, v[60:61], v[64:65] offset0:80 offset1:96
	ds_write2_b64 v53, v[62:63], v[66:67] offset0:208 offset1:224
	v_mfma_f32_16x16x32_bf16 v[42:45], v[42:45], v[22:25], 0
	s_nop 3
	v_mov_b32_e32 v56, v46
	s_nop 2
	v_mov_b32_e32 v57, v42
	v_mov_b32_e32 v42, v47
	ds_write2st64_b64 v55, v[56:57], v[42:43] offset0:8 offset1:9
	v_mov_b32_e32 v42, v48
	v_mov_b32_e32 v43, v44
	v_mov_b32_e32 v44, v49
	ds_write2st64_b64 v55, v[42:43], v[44:45] offset0:10 offset1:11
	s_waitcnt lgkmcnt(0)
	s_barrier
	ds_read2st64_b64 v[180:183], v51 offset0:8 offset1:9
	ds_read2st64_b64 v[184:187], v51 offset0:10 offset1:11
	ds_read2st64_b64 v[188:191], v51 offset0:12 offset1:13
	ds_read2st64_b64 v[192:195], v51 offset0:14 offset1:15
	ds_read2st64_b64 v[196:199], v51 offset0:16 offset1:17
	ds_read2st64_b64 v[200:203], v51 offset0:18 offset1:19
	ds_read2st64_b64 v[204:207], v51 offset0:20 offset1:21
	ds_read2st64_b64 v[208:211], v51 offset0:22 offset1:23
	v_xor_b32_e32 v46, 0x80000000, v69
	v_mov_b32_e32 v47, v68
	v_pk_mul_f32 v[46:47], v[52:53], v[46:47] op_sel_hi:[0,1]
	v_pk_fma_f32 v[46:47], v[50:51], v[68:69], v[46:47] op_sel_hi:[0,1,1]
	s_waitcnt lgkmcnt(7)
	v_pk_add_f32 v[42:43], v[180:181], v[46:47]
	v_mfma_f32_16x16x32_bf16 v[56:59], v[30:33], v[34:37], 0
	v_xor_b32_e32 v46, 0x80000000, v43
	v_mov_b32_e32 v47, v42
	v_pk_mul_f32 v[46:47], v[52:53], v[46:47] op_sel_hi:[0,1]
	v_pk_fma_f32 v[42:43], v[50:51], v[42:43], v[46:47] op_sel_hi:[0,1,1]
	v_pk_add_f32 v[46:47], v[182:183], v[42:43]
	v_xor_b32_e32 v48, 0x80000000, v47
	v_mov_b32_e32 v49, v46
	v_pk_mul_f32 v[48:49], v[52:53], v[48:49] op_sel_hi:[0,1]
	v_pk_fma_f32 v[46:47], v[50:51], v[46:47], v[48:49] op_sel_hi:[0,1,1]
	s_waitcnt lgkmcnt(6)
	v_pk_add_f32 v[42:43], v[184:185], v[46:47]
	v_mov_b32_e32 v67, v56
	v_xor_b32_e32 v46, 0x80000000, v43
	v_mov_b32_e32 v47, v42
	v_pk_mul_f32 v[46:47], v[52:53], v[46:47] op_sel_hi:[0,1]
	v_pk_fma_f32 v[42:43], v[50:51], v[42:43], v[46:47] op_sel_hi:[0,1,1]
	v_pk_add_f32 v[46:47], v[186:187], v[42:43]
	v_xor_b32_e32 v48, 0x80000000, v47
	v_mov_b32_e32 v49, v46
	v_pk_mul_f32 v[48:49], v[52:53], v[48:49] op_sel_hi:[0,1]
	v_pk_fma_f32 v[46:47], v[50:51], v[46:47], v[48:49] op_sel_hi:[0,1,1]
	s_waitcnt lgkmcnt(5)
	v_pk_add_f32 v[42:43], v[188:189], v[46:47]
	s_nop 0
	v_xor_b32_e32 v46, 0x80000000, v43
	v_mov_b32_e32 v47, v42
	v_pk_mul_f32 v[46:47], v[52:53], v[46:47] op_sel_hi:[0,1]
	v_pk_fma_f32 v[42:43], v[50:51], v[42:43], v[46:47] op_sel_hi:[0,1,1]
	v_pk_add_f32 v[46:47], v[190:191], v[42:43]
	v_xor_b32_e32 v48, 0x80000000, v47
	v_mov_b32_e32 v49, v46
	v_pk_mul_f32 v[48:49], v[52:53], v[48:49] op_sel_hi:[0,1]
	v_pk_fma_f32 v[46:47], v[50:51], v[46:47], v[48:49] op_sel_hi:[0,1,1]
	s_waitcnt lgkmcnt(4)
	v_pk_add_f32 v[42:43], v[192:193], v[46:47]
	s_nop 0
	v_xor_b32_e32 v46, 0x80000000, v43
	v_mov_b32_e32 v47, v42
	v_pk_mul_f32 v[46:47], v[52:53], v[46:47] op_sel_hi:[0,1]
	v_pk_fma_f32 v[42:43], v[50:51], v[42:43], v[46:47] op_sel_hi:[0,1,1]
	v_pk_add_f32 v[46:47], v[194:195], v[42:43]
	v_xor_b32_e32 v48, 0x80000000, v47
	v_mov_b32_e32 v49, v46
	v_pk_mul_f32 v[48:49], v[52:53], v[48:49] op_sel_hi:[0,1]
	v_pk_fma_f32 v[46:47], v[50:51], v[46:47], v[48:49] op_sel_hi:[0,1,1]
	s_waitcnt lgkmcnt(3)
	v_pk_add_f32 v[42:43], v[196:197], v[46:47]
	s_nop 0
	v_xor_b32_e32 v46, 0x80000000, v43
	v_mov_b32_e32 v47, v42
	v_pk_mul_f32 v[46:47], v[52:53], v[46:47] op_sel_hi:[0,1]
	v_pk_fma_f32 v[42:43], v[50:51], v[42:43], v[46:47] op_sel_hi:[0,1,1]
	v_pk_add_f32 v[46:47], v[198:199], v[42:43]
	v_xor_b32_e32 v48, 0x80000000, v47
	v_mov_b32_e32 v49, v46
	v_pk_mul_f32 v[48:49], v[52:53], v[48:49] op_sel_hi:[0,1]
	v_pk_fma_f32 v[46:47], v[50:51], v[46:47], v[48:49] op_sel_hi:[0,1,1]
	s_waitcnt lgkmcnt(2)
	v_pk_add_f32 v[42:43], v[200:201], v[46:47]
	s_nop 0
	v_xor_b32_e32 v46, 0x80000000, v43
	v_mov_b32_e32 v47, v42
	v_pk_mul_f32 v[46:47], v[52:53], v[46:47] op_sel_hi:[0,1]
	v_pk_fma_f32 v[42:43], v[50:51], v[42:43], v[46:47] op_sel_hi:[0,1,1]
	v_pk_add_f32 v[46:47], v[202:203], v[42:43]
	v_xor_b32_e32 v48, 0x80000000, v47
	v_mov_b32_e32 v49, v46
	v_pk_mul_f32 v[48:49], v[52:53], v[48:49] op_sel_hi:[0,1]
	v_pk_fma_f32 v[46:47], v[50:51], v[46:47], v[48:49] op_sel_hi:[0,1,1]
	s_waitcnt lgkmcnt(1)
	v_pk_add_f32 v[42:43], v[204:205], v[46:47]
	s_nop 0
	v_xor_b32_e32 v46, 0x80000000, v43
	v_mov_b32_e32 v47, v42
	v_pk_mul_f32 v[46:47], v[52:53], v[46:47] op_sel_hi:[0,1]
	v_pk_fma_f32 v[42:43], v[50:51], v[42:43], v[46:47] op_sel_hi:[0,1,1]
	v_pk_add_f32 v[46:47], v[206:207], v[42:43]
	v_xor_b32_e32 v48, 0x80000000, v47
	v_mov_b32_e32 v49, v46
	v_pk_mul_f32 v[48:49], v[52:53], v[48:49] op_sel_hi:[0,1]
	v_pk_fma_f32 v[46:47], v[50:51], v[46:47], v[48:49] op_sel_hi:[0,1,1]
	s_waitcnt lgkmcnt(0)
	v_pk_add_f32 v[42:43], v[208:209], v[46:47]
	s_nop 0
	v_xor_b32_e32 v46, 0x80000000, v43
	v_mov_b32_e32 v47, v42
	v_pk_mul_f32 v[46:47], v[52:53], v[46:47] op_sel_hi:[0,1]
	v_pk_fma_f32 v[42:43], v[50:51], v[42:43], v[46:47] op_sel_hi:[0,1,1]
	v_pk_add_f32 v[64:65], v[210:211], v[42:43]
	v_mfma_f32_16x16x32_bf16 v[42:45], v[30:33], v[26:29], 0
	s_barrier
; __device__ __forceinline__ void s5_bu16(const S5Frag& f, const bf16x8 uf, float* buL, int lane) {
;     const int jj = lane & 15, quad = lane >> 4;
; #pragma unroll
;     for (int nt = 0; nt < 4; ++nt) {
;         const f32x4 z = (f32x4){0.f, 0.f, 0.f, 0.f};
;         const f32x4 dre = __builtin_amdgcn_mfma_f32_16x16x32_bf16(uf, f.bfr[nt], z, 0, 0, 0);
;         const f32x4 dim = __builtin_amdgcn_mfma_f32_16x16x32_bf16(uf, f.bfr[nt + 4], z, 0, 0, 0);
; #pragma unroll
;         for (int r = 0; r < 4; ++r) *(f32x2*)(buL + ((4 * quad + r) * 64 + 16 * nt + jj) * 2) = (f32x2){dre[r], dim[r]};
;     }
; __device__ __forceinline__ void s5_pass1_item(PP p, unsigned char* shm, int item, int l) {
;     ...
;     for (int sc = 0; sc < 4; ++sc) {
;         s5_bu16(f, uf[sc], buL, lane);
;         __syncthreads();
; #pragma unroll
;         for (int t = 0; t < 16; ++t) s5_rec(q, *(const f32x2*)(buL + (t * 64 + lane) * 2), x);
	v_mfma_f32_16x16x32_bf16 v[46:49], v[30:33], v[38:41], 0
	v_mfma_f32_16x16x32_bf16 v[26:29], v[2:5], v[26:29], 0
	s_nop 4
	v_mov_b32_e32 v60, v42
	s_nop 0
	v_mov_b32_e32 v61, v46
	v_mov_b32_e32 v46, v43
	v_mov_b32_e32 v62, v44
	v_mov_b32_e32 v63, v48
	v_mov_b32_e32 v48, v45
	v_mfma_f32_16x16x32_bf16 v[42:45], v[30:33], v[14:17], 0
	v_mfma_f32_16x16x32_bf16 v[14:17], v[2:5], v[14:17], 0
	s_nop 6
	v_mov_b32_e32 v66, v42
	v_mov_b32_e32 v56, v43
	v_mov_b32_e32 v42, v44
	v_mov_b32_e32 v43, v58
	ds_write2_b64 v53, v[60:61], v[66:67] offset1:16
	ds_write2_b64 v53, v[62:63], v[42:43] offset0:128 offset1:144
	v_mov_b32_e32 v58, v45
	v_mfma_f32_16x16x32_bf16 v[42:45], v[30:33], v[6:9], 0
	v_mfma_f32_16x16x32_bf16 v[60:63], v[30:33], v[18:21], 0
	v_mfma_f32_16x16x32_bf16 v[6:9], v[2:5], v[6:9], 0
	s_nop 5
	v_mov_b32_e32 v66, v42
	v_mov_b32_e32 v67, v60
	v_mov_b32_e32 v60, v43
	v_mov_b32_e32 v42, v44
	v_mov_b32_e32 v43, v62
	ds_write2_b64 v53, v[42:43], v[48:49] offset0:160 offset1:192
	v_mov_b32_e32 v62, v45
	v_mfma_f32_16x16x32_bf16 v[42:45], v[30:33], v[10:13], 0
	ds_write2_b64 v53, v[66:67], v[46:47] offset0:32 offset1:64
	ds_write2_b64 v53, v[56:57], v[60:61] offset0:80 offset1:96
	ds_write2_b64 v53, v[58:59], v[62:63] offset0:208 offset1:224
	v_mfma_f32_16x16x32_bf16 v[30:33], v[30:33], v[22:25], 0
	s_nop 3
	v_mov_b32_e32 v46, v42
	s_nop 2
	v_mov_b32_e32 v47, v30
	v_mov_b32_e32 v30, v43
	ds_write2st64_b64 v55, v[46:47], v[30:31] offset0:8 offset1:9
	v_mov_b32_e32 v30, v44
	v_mov_b32_e32 v31, v32
	v_mov_b32_e32 v32, v45
	ds_write2st64_b64 v55, v[30:31], v[32:33] offset0:10 offset1:11
	s_waitcnt lgkmcnt(0)
	s_barrier
	ds_read2st64_b64 v[180:183], v51 offset0:8 offset1:9
	ds_read2st64_b64 v[184:187], v51 offset0:10 offset1:11
	ds_read2st64_b64 v[188:191], v51 offset0:12 offset1:13
	ds_read2st64_b64 v[192:195], v51 offset0:14 offset1:15
	ds_read2st64_b64 v[196:199], v51 offset0:16 offset1:17
	ds_read2st64_b64 v[200:203], v51 offset0:18 offset1:19
	ds_read2st64_b64 v[204:207], v51 offset0:20 offset1:21
	ds_read2st64_b64 v[208:211], v51 offset0:22 offset1:23
	v_xor_b32_e32 v42, 0x80000000, v65
	v_mov_b32_e32 v43, v64
	v_pk_mul_f32 v[42:43], v[52:53], v[42:43] op_sel_hi:[0,1]
	v_pk_fma_f32 v[42:43], v[50:51], v[64:65], v[42:43] op_sel_hi:[0,1,1]
	s_waitcnt lgkmcnt(7)
	v_pk_add_f32 v[30:31], v[180:181], v[42:43]
	s_nop 0
	v_xor_b32_e32 v42, 0x80000000, v31
	v_mov_b32_e32 v43, v30
	v_pk_mul_f32 v[42:43], v[52:53], v[42:43] op_sel_hi:[0,1]
	v_pk_fma_f32 v[30:31], v[50:51], v[30:31], v[42:43] op_sel_hi:[0,1,1]
	v_pk_add_f32 v[42:43], v[182:183], v[30:31]
	v_xor_b32_e32 v44, 0x80000000, v43
	v_mov_b32_e32 v45, v42
	v_pk_mul_f32 v[44:45], v[52:53], v[44:45] op_sel_hi:[0,1]
	v_pk_fma_f32 v[42:43], v[50:51], v[42:43], v[44:45] op_sel_hi:[0,1,1]
	s_waitcnt lgkmcnt(6)
	v_pk_add_f32 v[30:31], v[184:185], v[42:43]
	s_nop 0
	v_xor_b32_e32 v42, 0x80000000, v31
	v_mov_b32_e32 v43, v30
	v_pk_mul_f32 v[42:43], v[52:53], v[42:43] op_sel_hi:[0,1]
	v_pk_fma_f32 v[30:31], v[50:51], v[30:31], v[42:43] op_sel_hi:[0,1,1]
	v_pk_add_f32 v[42:43], v[186:187], v[30:31]
	v_xor_b32_e32 v44, 0x80000000, v43
	v_mov_b32_e32 v45, v42
	v_pk_mul_f32 v[44:45], v[52:53], v[44:45] op_sel_hi:[0,1]
	v_pk_fma_f32 v[42:43], v[50:51], v[42:43], v[44:45] op_sel_hi:[0,1,1]
	s_waitcnt lgkmcnt(5)
	v_pk_add_f32 v[30:31], v[188:189], v[42:43]
	s_nop 0
	v_xor_b32_e32 v42, 0x80000000, v31
	v_mov_b32_e32 v43, v30
	v_pk_mul_f32 v[42:43], v[52:53], v[42:43] op_sel_hi:[0,1]
	v_pk_fma_f32 v[30:31], v[50:51], v[30:31], v[42:43] op_sel_hi:[0,1,1]
	v_pk_add_f32 v[42:43], v[190:191], v[30:31]
	v_xor_b32_e32 v44, 0x80000000, v43
	v_mov_b32_e32 v45, v42
	v_pk_mul_f32 v[44:45], v[52:53], v[44:45] op_sel_hi:[0,1]
	v_pk_fma_f32 v[42:43], v[50:51], v[42:43], v[44:45] op_sel_hi:[0,1,1]
	s_waitcnt lgkmcnt(4)
	v_pk_add_f32 v[30:31], v[192:193], v[42:43]
	s_nop 0
	v_xor_b32_e32 v42, 0x80000000, v31
	v_mov_b32_e32 v43, v30
	v_pk_mul_f32 v[42:43], v[52:53], v[42:43] op_sel_hi:[0,1]
	v_pk_fma_f32 v[30:31], v[50:51], v[30:31], v[42:43] op_sel_hi:[0,1,1]
	v_pk_add_f32 v[42:43], v[194:195], v[30:31]
	v_xor_b32_e32 v44, 0x80000000, v43
	v_mov_b32_e32 v45, v42
	v_pk_mul_f32 v[44:45], v[52:53], v[44:45] op_sel_hi:[0,1]
	v_pk_fma_f32 v[42:43], v[50:51], v[42:43], v[44:45] op_sel_hi:[0,1,1]
	s_waitcnt lgkmcnt(3)
	v_pk_add_f32 v[30:31], v[196:197], v[42:43]
	s_nop 0
	v_xor_b32_e32 v42, 0x80000000, v31
	v_mov_b32_e32 v43, v30
	v_pk_mul_f32 v[42:43], v[52:53], v[42:43] op_sel_hi:[0,1]
	v_pk_fma_f32 v[30:31], v[50:51], v[30:31], v[42:43] op_sel_hi:[0,1,1]
	v_pk_add_f32 v[42:43], v[198:199], v[30:31]
	v_xor_b32_e32 v44, 0x80000000, v43
	v_mov_b32_e32 v45, v42
	v_pk_mul_f32 v[44:45], v[52:53], v[44:45] op_sel_hi:[0,1]
	v_pk_fma_f32 v[42:43], v[50:51], v[42:43], v[44:45] op_sel_hi:[0,1,1]
	s_waitcnt lgkmcnt(2)
	v_pk_add_f32 v[30:31], v[200:201], v[42:43]
	s_nop 0
	v_xor_b32_e32 v42, 0x80000000, v31
	v_mov_b32_e32 v43, v30
	v_pk_mul_f32 v[42:43], v[52:53], v[42:43] op_sel_hi:[0,1]
	v_pk_fma_f32 v[30:31], v[50:51], v[30:31], v[42:43] op_sel_hi:[0,1,1]
	v_pk_add_f32 v[42:43], v[202:203], v[30:31]
	v_xor_b32_e32 v44, 0x80000000, v43
	v_mov_b32_e32 v45, v42
	v_pk_mul_f32 v[44:45], v[52:53], v[44:45] op_sel_hi:[0,1]
	v_pk_fma_f32 v[42:43], v[50:51], v[42:43], v[44:45] op_sel_hi:[0,1,1]
	s_waitcnt lgkmcnt(1)
	v_pk_add_f32 v[30:31], v[204:205], v[42:43]
	s_nop 0
	v_xor_b32_e32 v42, 0x80000000, v31
	v_mov_b32_e32 v43, v30
	v_pk_mul_f32 v[42:43], v[52:53], v[42:43] op_sel_hi:[0,1]
	v_pk_fma_f32 v[30:31], v[50:51], v[30:31], v[42:43] op_sel_hi:[0,1,1]
	v_pk_add_f32 v[42:43], v[206:207], v[30:31]
	v_xor_b32_e32 v44, 0x80000000, v43
	v_mov_b32_e32 v45, v42
	v_pk_mul_f32 v[44:45], v[52:53], v[44:45] op_sel_hi:[0,1]
	v_pk_fma_f32 v[42:43], v[50:51], v[42:43], v[44:45] op_sel_hi:[0,1,1]
	s_waitcnt lgkmcnt(0)
	v_pk_add_f32 v[30:31], v[208:209], v[42:43]
	s_nop 0
	v_xor_b32_e32 v42, 0x80000000, v31
	v_mov_b32_e32 v43, v30
	v_pk_mul_f32 v[42:43], v[52:53], v[42:43] op_sel_hi:[0,1]
	v_pk_fma_f32 v[30:31], v[50:51], v[30:31], v[42:43] op_sel_hi:[0,1,1]
	v_pk_add_f32 v[42:43], v[210:211], v[30:31]
	v_mfma_f32_16x16x32_bf16 v[30:33], v[2:5], v[38:41], 0
	v_mov_b32_e32 v38, v26
	v_mov_b32_e32 v40, v28
	s_barrier
; __device__ __forceinline__ void s5_pass1_item(PP p, unsigned char* shm, int item, int l) {
;     ...
;     for (int sc = 0; sc < 4; ++sc) {
;         s5_bu16(f, uf[sc], buL, lane);
;         __syncthreads();
; #pragma unroll
;         for (int t = 0; t < 16; ++t) s5_rec(q, *(const f32x2*)(buL + (t * 64 + lane) * 2), x);
;         __syncthreads();
;     }
;     *(f32x2*)((float*)(p->ws + WS_CARRY) + ((size_t)((b * 32 + g) * 32 + j) * 64 + lane) * 2) = x;
	s_nop 4
	v_mov_b32_e32 v39, v30
	v_mov_b32_e32 v30, v27
	v_mov_b32_e32 v41, v32
	v_mov_b32_e32 v32, v29
	v_mfma_f32_16x16x32_bf16 v[26:29], v[2:5], v[34:37], 0
	v_mov_b32_e32 v34, v14
	v_mov_b32_e32 v14, v16
	s_nop 5
	v_mov_b32_e32 v35, v26
	v_mov_b32_e32 v26, v15
	v_mov_b32_e32 v15, v28
	ds_write2_b64 v53, v[40:41], v[14:15] offset0:128 offset1:144
	v_mov_b32_e32 v28, v17
	v_mfma_f32_16x16x32_bf16 v[14:17], v[2:5], v[18:21], 0
	v_mov_b32_e32 v18, v6
	v_mov_b32_e32 v6, v8
	ds_write2_b64 v53, v[38:39], v[34:35] offset1:16
	s_nop 4
	v_mov_b32_e32 v19, v14
	v_mov_b32_e32 v14, v7
	v_mov_b32_e32 v7, v16
	ds_write2_b64 v53, v[6:7], v[32:33] offset0:160 offset1:192
	v_mov_b32_e32 v16, v9
	v_mfma_f32_16x16x32_bf16 v[6:9], v[2:5], v[10:13], 0
	ds_write2_b64 v53, v[18:19], v[30:31] offset0:32 offset1:64
	ds_write2_b64 v53, v[26:27], v[14:15] offset0:80 offset1:96
	ds_write2_b64 v53, v[28:29], v[16:17] offset0:208 offset1:224
	v_mfma_f32_16x16x32_bf16 v[2:5], v[2:5], v[22:25], 0
	s_nop 3
	v_mov_b32_e32 v10, v6
	s_nop 2
	v_mov_b32_e32 v11, v2
	v_mov_b32_e32 v2, v7
	ds_write2st64_b64 v55, v[10:11], v[2:3] offset0:8 offset1:9
	v_mov_b32_e32 v2, v8
	v_mov_b32_e32 v3, v4
	v_mov_b32_e32 v4, v9
	ds_write2st64_b64 v55, v[2:3], v[4:5] offset0:10 offset1:11
	s_waitcnt lgkmcnt(0)
	s_barrier
	ds_read2st64_b64 v[180:183], v51 offset0:8 offset1:9
	ds_read2st64_b64 v[184:187], v51 offset0:10 offset1:11
	ds_read2st64_b64 v[188:191], v51 offset0:12 offset1:13
	ds_read2st64_b64 v[192:195], v51 offset0:14 offset1:15
	ds_read2st64_b64 v[196:199], v51 offset0:16 offset1:17
	ds_read2st64_b64 v[200:203], v51 offset0:18 offset1:19
	ds_read2st64_b64 v[204:207], v51 offset0:20 offset1:21
	ds_read2st64_b64 v[208:211], v51 offset0:22 offset1:23
	v_xor_b32_e32 v6, 0x80000000, v43
	v_mov_b32_e32 v7, v42
	v_pk_mul_f32 v[6:7], v[52:53], v[6:7] op_sel_hi:[0,1]
	v_pk_fma_f32 v[6:7], v[50:51], v[42:43], v[6:7] op_sel_hi:[0,1,1]
	s_waitcnt lgkmcnt(7)
	v_pk_add_f32 v[2:3], v[180:181], v[6:7]
	s_nop 0
	v_xor_b32_e32 v6, 0x80000000, v3
	v_mov_b32_e32 v7, v2
	v_pk_mul_f32 v[6:7], v[52:53], v[6:7] op_sel_hi:[0,1]
	v_pk_fma_f32 v[2:3], v[50:51], v[2:3], v[6:7] op_sel_hi:[0,1,1]
	v_pk_add_f32 v[6:7], v[182:183], v[2:3]
	v_xor_b32_e32 v8, 0x80000000, v7
	v_mov_b32_e32 v9, v6
	v_pk_mul_f32 v[8:9], v[52:53], v[8:9] op_sel_hi:[0,1]
	v_pk_fma_f32 v[6:7], v[50:51], v[6:7], v[8:9] op_sel_hi:[0,1,1]
	s_waitcnt lgkmcnt(6)
	v_pk_add_f32 v[2:3], v[184:185], v[6:7]
	s_nop 0
	v_xor_b32_e32 v6, 0x80000000, v3
	v_mov_b32_e32 v7, v2
	v_pk_mul_f32 v[6:7], v[52:53], v[6:7] op_sel_hi:[0,1]
	v_pk_fma_f32 v[2:3], v[50:51], v[2:3], v[6:7] op_sel_hi:[0,1,1]
	v_pk_add_f32 v[6:7], v[186:187], v[2:3]
	v_xor_b32_e32 v8, 0x80000000, v7
	v_mov_b32_e32 v9, v6
	v_pk_mul_f32 v[8:9], v[52:53], v[8:9] op_sel_hi:[0,1]
	v_pk_fma_f32 v[6:7], v[50:51], v[6:7], v[8:9] op_sel_hi:[0,1,1]
	s_waitcnt lgkmcnt(5)
	v_pk_add_f32 v[2:3], v[188:189], v[6:7]
	s_nop 0
	v_xor_b32_e32 v6, 0x80000000, v3
	v_mov_b32_e32 v7, v2
	v_pk_mul_f32 v[6:7], v[52:53], v[6:7] op_sel_hi:[0,1]
	v_pk_fma_f32 v[2:3], v[50:51], v[2:3], v[6:7] op_sel_hi:[0,1,1]
	v_pk_add_f32 v[6:7], v[190:191], v[2:3]
	v_xor_b32_e32 v8, 0x80000000, v7
	v_mov_b32_e32 v9, v6
	v_pk_mul_f32 v[8:9], v[52:53], v[8:9] op_sel_hi:[0,1]
	v_pk_fma_f32 v[6:7], v[50:51], v[6:7], v[8:9] op_sel_hi:[0,1,1]
	s_waitcnt lgkmcnt(4)
	v_pk_add_f32 v[2:3], v[192:193], v[6:7]
	s_nop 0
	v_xor_b32_e32 v6, 0x80000000, v3
	v_mov_b32_e32 v7, v2
	v_pk_mul_f32 v[6:7], v[52:53], v[6:7] op_sel_hi:[0,1]
	v_pk_fma_f32 v[2:3], v[50:51], v[2:3], v[6:7] op_sel_hi:[0,1,1]
	v_pk_add_f32 v[6:7], v[194:195], v[2:3]
	v_xor_b32_e32 v8, 0x80000000, v7
	v_mov_b32_e32 v9, v6
	v_pk_mul_f32 v[8:9], v[52:53], v[8:9] op_sel_hi:[0,1]
	v_pk_fma_f32 v[6:7], v[50:51], v[6:7], v[8:9] op_sel_hi:[0,1,1]
	s_waitcnt lgkmcnt(3)
	v_pk_add_f32 v[2:3], v[196:197], v[6:7]
	s_nop 0
	v_xor_b32_e32 v6, 0x80000000, v3
	v_mov_b32_e32 v7, v2
	v_pk_mul_f32 v[6:7], v[52:53], v[6:7] op_sel_hi:[0,1]
	v_pk_fma_f32 v[2:3], v[50:51], v[2:3], v[6:7] op_sel_hi:[0,1,1]
	v_pk_add_f32 v[6:7], v[198:199], v[2:3]
	v_xor_b32_e32 v8, 0x80000000, v7
	v_mov_b32_e32 v9, v6
	v_pk_mul_f32 v[8:9], v[52:53], v[8:9] op_sel_hi:[0,1]
	v_pk_fma_f32 v[6:7], v[50:51], v[6:7], v[8:9] op_sel_hi:[0,1,1]
	s_waitcnt lgkmcnt(2)
	v_pk_add_f32 v[2:3], v[200:201], v[6:7]
	s_nop 0
	v_xor_b32_e32 v6, 0x80000000, v3
	v_mov_b32_e32 v7, v2
	v_pk_mul_f32 v[6:7], v[52:53], v[6:7] op_sel_hi:[0,1]
	v_pk_fma_f32 v[2:3], v[50:51], v[2:3], v[6:7] op_sel_hi:[0,1,1]
	v_pk_add_f32 v[6:7], v[202:203], v[2:3]
	v_xor_b32_e32 v8, 0x80000000, v7
	v_mov_b32_e32 v9, v6
	v_pk_mul_f32 v[8:9], v[52:53], v[8:9] op_sel_hi:[0,1]
	v_pk_fma_f32 v[6:7], v[50:51], v[6:7], v[8:9] op_sel_hi:[0,1,1]
	s_waitcnt lgkmcnt(1)
	v_pk_add_f32 v[2:3], v[204:205], v[6:7]
	s_nop 0
	v_xor_b32_e32 v6, 0x80000000, v3
	v_mov_b32_e32 v7, v2
	v_pk_mul_f32 v[6:7], v[52:53], v[6:7] op_sel_hi:[0,1]
	v_pk_fma_f32 v[2:3], v[50:51], v[2:3], v[6:7] op_sel_hi:[0,1,1]
	v_pk_add_f32 v[6:7], v[206:207], v[2:3]
	v_xor_b32_e32 v8, 0x80000000, v7
	v_mov_b32_e32 v9, v6
	v_pk_mul_f32 v[8:9], v[52:53], v[8:9] op_sel_hi:[0,1]
	v_pk_fma_f32 v[6:7], v[50:51], v[6:7], v[8:9] op_sel_hi:[0,1,1]
	s_waitcnt lgkmcnt(0)
	v_pk_add_f32 v[2:3], v[208:209], v[6:7]
	s_nop 0
	v_xor_b32_e32 v6, 0x80000000, v3
	v_mov_b32_e32 v7, v2
	v_pk_mul_f32 v[6:7], v[52:53], v[6:7] op_sel_hi:[0,1]
	v_pk_fma_f32 v[2:3], v[50:51], v[2:3], v[6:7] op_sel_hi:[0,1,1]
	v_pk_add_f32 v[2:3], v[210:211], v[2:3]
	v_add_u32_e32 v4, s3, v54
	v_ashrrev_i32_e32 v5, 31, v4
	v_lshlrev_b64 v[4:5], 9, v[4:5]
	v_lshl_add_u64 v[4:5], s[12:13], 0, v[4:5]
	v_lshl_add_u64 v[4:5], v[4:5], 0, v[0:1]
	v_add_co_u32_e32 v4, vcc, 0x31ac0000, v4
	s_barrier
	s_nop 0
	v_addc_co_u32_e32 v5, vcc, 0, v5, vcc
	global_store_dwordx2 v[4:5], v[2:3], off

; __device__ __forceinline__ void s5_pass2_item(PP p, unsigned char* shm, int item, int l) {
;     ...
;     { const float* src = ((quad < 2) ? p->in[11] : p->in[12]) + ((size_t)(l * 32 + g) * 16 + cc) * 64 + (quad & 1) * 32;
;       const float sgn = (quad < 2) ? 1.0f : -1.0f;
; #pragma unroll
;       for (int i = 0; i < 8; ++i) { const f32x4 v = *(const f32x4*)(src + 4 * i); cmr[4 * i] = v[0] * sgn; cmr[4 * i + 1] = v[1] * sgn; cmr[4 * i + 2] = v[2] * sgn; cmr[4 * i + 3] = v[3] * sgn; } }
;     S5Lane q; s5_lane_params(p, l, g, lane, q);
;     const size_t row0 = (size_t)b * SEQ + j * 64;
;     bf16x8 uf[4];
; #pragma unroll
;     for (int sc = 0; sc < 4; ++sc) uf[sc] = s5_ufrag(proj, row0 + sc * 16, g, lane);
;     s5_write_bbl(q, bbL, lane);
;     float pr = q.ar, pi = q.ai;
; #pragma unroll
;     for (int s = 0; s < 6; ++s) { const float nr = pr * pr - pi * pi, ni = 2.f * pr * pi; pr = nr; pi = ni; }
;     f32x2 x = (f32x2){0.f, 0.f};
;     const f32x2* carry = (const f32x2*)((const float*)(p->ws + WS_CARRY) + ((size_t)((b * 32 + g) * 32) * 64 + lane) * 2);
;     for (int i0 = 0; i0 < j; i0 += 8) {
;         f32x2 sv[8];
; #pragma unroll
;         for (int e = 0; e < 8; ++e) sv[e] = (i0 + e < j) ? carry[(size_t)(i0 + e) * 64] : (f32x2){0.f, 0.f};
; #pragma unroll
;         for (int e = 0; e < 8; ++e) if (i0 + e < j) { const f32x2 rot = (f32x2){-x.y, x.x}; x = (x * pr + rot * pi) + sv[e]; }
;     }
;     __syncthreads();
;     S5Frag f; s5_load_frags(bbL, f, lane);
;     const float dsk = p->in[13][(size_t)l * 512 + g * 16 + cc];
;     bf16_t* Gout = (bf16_t*)(p->ws + WS_GPH);
;     for (int sc = 0; sc < 4; ++sc) {
;         s5_bu16(f, uf[sc], buL, lane);
;         __syncthreads();
; #pragma unroll
;         for (int t = 0; t < 16; ++t) { s5_rec(q, *(const f32x2*)(buL + (t * 64 + lane) * 2), x); xs[t * 132 + lane] = x.x; xs[t * 132 + 64 + lane] = x.y; }
.LBB0_679:
	s_or_b64 exec, exec, s[2:3]
	s_movk_i32 s2, 0x2100
	v_mul_lo_u32 v0, v93, s2
	s_add_i32 s2, 0, 0x11000
	v_add_u32_e32 v102, s2, v0
	s_load_dwordx2 s[2:3], s[12:13], 0x68
	v_lshl_add_u32 v0, v93, 13, 0
	v_mul_f32_e32 v77, v77, v97
	v_mul_f32_e32 v76, v76, v97
	v_mul_f32_e32 v75, v75, v97
	s_waitcnt lgkmcnt(0)
	s_add_u32 s12, s2, s18
	s_addc_u32 s13, s3, 0
	s_lshl_b64 s[2:3], s[34:35], 2
	s_add_u32 s2, s12, s2
	v_mul_f32_e32 v74, v74, v97
	v_mul_f32_e32 v73, v73, v97
	v_mul_f32_e32 v72, v72, v97
	v_mul_f32_e32 v71, v71, v97
	v_mul_f32_e32 v70, v70, v97
	v_mul_f32_e32 v69, v69, v97
	v_mul_f32_e32 v68, v68, v97
	v_mul_f32_e32 v67, v67, v97
	v_mul_f32_e32 v66, v66, v97
	v_mul_f32_e32 v65, v65, v97
	v_mul_f32_e32 v64, v64, v97
	v_mul_f32_e32 v63, v63, v97
	v_mul_f32_e32 v62, v62, v97
	v_mul_f32_e32 v61, v61, v97
	v_mul_f32_e32 v60, v60, v97
	v_mul_f32_e32 v59, v59, v97
	v_mul_f32_e32 v58, v58, v97
	v_mul_f32_e32 v57, v57, v97
	v_mul_f32_e32 v56, v56, v97
	v_mul_f32_e32 v55, v55, v97
	v_mul_f32_e32 v85, v54, v97
	v_mul_f32_e32 v88, v53, v97
	v_mul_f32_e32 v91, v52, v97
	v_mul_f32_e32 v92, v51, v97
	v_mul_f32_e32 v93, v50, v97
	v_mul_f32_e32 v94, v49, v97
	v_mul_f32_e32 v95, v48, v97
	v_mul_f32_e32 v96, v47, v97
	v_mul_f32_e32 v97, v46, v97
	s_addc_u32 s3, s13, s3
	v_lshlrev_b32_e32 v46, 2, v100
	global_load_dword v54, v46, s[2:3]
	v_and_b32_e32 v46, 0x600, v99
	v_lshl_add_u32 v46, v46, 2, v0
	v_and_b32_e32 v47, 0x78, v90
	v_add_u32_e32 v108, v46, v47
	v_or_b32_e32 v47, 0x180, v90
	v_add_u32_e32 v99, v46, v47
	v_mul_u32_u24_e32 v46, 0x210, v100
	v_lshlrev_b32_e32 v47, 2, v101
	v_add_u32_e32 v90, v0, v90
	v_mov_b32_e32 v0, v89
	v_lshl_add_u32 v98, v98, 2, v102
	v_add3_u32 v89, v102, v46, v47
	v_or_b32_e32 v50, s34, v100
	v_mfma_f32_16x16x32_bf16 v[46:49], v[78:81], v[26:29], 0
	v_add_u32_e32 v108, 0x1000, v108
	v_lshl_or_b32 v82, v109, 2, v82
	v_mov_b32_e32 v51, s35
	v_mfma_f32_16x16x32_bf16 v[100:103], v[78:81], v[34:37], 0
	s_add_u32 s28, s28, 0x21600000
	s_nop 2
	v_mov_b32_e32 v52, v46
	v_mov_b32_e32 v110, v48
	v_mfma_f32_16x16x32_bf16 v[104:107], v[78:81], v[30:33], 0
	s_addc_u32 s29, s29, 0
	v_mov_b32_e32 v53, v100
	v_mov_b32_e32 v100, v47
	v_mov_b32_e32 v111, v102
	v_mov_b32_e32 v102, v49
	v_mfma_f32_16x16x32_bf16 v[46:49], v[78:81], v[22:25], 0
	s_nop 1
	v_mov_b32_e32 v113, v104
	s_xor_b32 s14, s14, 3
	s_add_i32 s14, s14, s66
	s_cmpk_gt_i32 s14, 0x1ff
	s_nop 2
	v_mov_b32_e32 v112, v46
	v_mov_b32_e32 v104, v47
	v_mov_b32_e32 v46, v48
	v_mov_b32_e32 v47, v106
	ds_write2_b64 v108, v[52:53], v[112:113] offset1:16
	ds_write2_b64 v108, v[110:111], v[46:47] offset0:128 offset1:144
	v_mov_b32_e32 v106, v49
	v_mfma_f32_16x16x32_bf16 v[46:49], v[78:81], v[18:21], 0
	v_mfma_f32_16x16x32_bf16 v[110:113], v[78:81], v[14:17], 0
	s_nop 6
	v_mov_b32_e32 v52, v46
	v_mov_b32_e32 v53, v110
	v_mov_b32_e32 v110, v47
	v_mov_b32_e32 v46, v48
	v_mov_b32_e32 v47, v112
	ds_write2_b64 v108, v[46:47], v[102:103] offset0:160 offset1:192
	v_mov_b32_e32 v112, v49
	v_mfma_f32_16x16x32_bf16 v[46:49], v[78:81], v[10:13], 0
	ds_write2_b64 v108, v[52:53], v[100:101] offset0:32 offset1:64
	ds_write2_b64 v108, v[104:105], v[110:111] offset0:80 offset1:96
	ds_write2_b64 v108, v[106:107], v[112:113] offset0:208 offset1:224
	v_mfma_f32_16x16x32_bf16 v[78:81], v[78:81], v[6:9], 0
	v_add_u32_e32 v100, 0x80, v98
	s_nop 2
	v_mov_b32_e32 v52, v46
	v_mov_b32_e32 v46, v48
	v_xor_b32_e32 v48, 0x80000000, v87
	v_add_u32_e32 v101, 0x90, v98
	v_mov_b32_e32 v53, v78
	v_mov_b32_e32 v78, v47
	v_mov_b32_e32 v47, v80
	v_mov_b32_e32 v80, v49
	ds_write2st64_b64 v99, v[52:53], v[78:79] offset0:8 offset1:9
	ds_write2st64_b64 v99, v[46:47], v[80:81] offset0:10 offset1:11
	s_waitcnt lgkmcnt(0)
	s_barrier
	ds_read_b64 v[140:141], v90 offset:4096
	ds_read_b64 v[142:143], v90 offset:4608
	ds_read_b64 v[144:145], v90 offset:5120
	ds_read_b64 v[146:147], v90 offset:5632
	ds_read_b64 v[148:149], v90 offset:6144
	ds_read_b64 v[150:151], v90 offset:6656
	ds_read_b64 v[152:153], v90 offset:7168
	ds_read_b64 v[154:155], v90 offset:7680
	v_mov_b32_e32 v49, v86
	v_pk_mul_f32 v[48:49], v[0:1], v[48:49] op_sel_hi:[0,1]
	v_pk_fma_f32 v[48:49], v[84:85], v[86:87], v[48:49] op_sel_hi:[0,1,1]
	v_add_u32_e32 v78, 32, v98
	s_waitcnt lgkmcnt(7)
	v_pk_add_f32 v[46:47], v[48:49], v[140:141]
	ds_write2st64_b32 v98, v46, v47 offset1:1
	v_xor_b32_e32 v52, 0x80000000, v47
	v_mov_b32_e32 v53, v46
	v_pk_mul_f32 v[52:53], v[0:1], v[52:53] op_sel_hi:[0,1]
	v_pk_fma_f32 v[46:47], v[84:85], v[46:47], v[52:53] op_sel_hi:[0,1,1]
	s_waitcnt lgkmcnt(7)
	v_pk_add_f32 v[46:47], v[142:143], v[46:47]
	ds_write2_b32 v98, v46, v47 offset0:132 offset1:196
	v_xor_b32_e32 v52, 0x80000000, v47
	v_mov_b32_e32 v53, v46
	v_pk_mul_f32 v[52:53], v[0:1], v[52:53] op_sel_hi:[0,1]
	v_pk_fma_f32 v[46:47], v[84:85], v[46:47], v[52:53] op_sel_hi:[0,1,1]
	s_waitcnt lgkmcnt(7)
	v_pk_add_f32 v[46:47], v[144:145], v[46:47]
	ds_write2st64_b32 v78, v46, v47 offset0:4 offset1:5
	v_xor_b32_e32 v52, 0x80000000, v47
	v_mov_b32_e32 v53, v46
	v_pk_mul_f32 v[52:53], v[0:1], v[52:53] op_sel_hi:[0,1]
	v_pk_fma_f32 v[46:47], v[84:85], v[46:47], v[52:53] op_sel_hi:[0,1,1]
	s_waitcnt lgkmcnt(7)
	v_pk_add_f32 v[46:47], v[146:147], v[46:47]
	v_add_u32_e32 v79, 48, v98
	ds_write2st64_b32 v79, v46, v47 offset0:6 offset1:7
	v_xor_b32_e32 v52, 0x80000000, v47
	v_mov_b32_e32 v53, v46
	v_pk_mul_f32 v[52:53], v[0:1], v[52:53] op_sel_hi:[0,1]
	v_pk_fma_f32 v[46:47], v[84:85], v[46:47], v[52:53] op_sel_hi:[0,1,1]
	s_waitcnt lgkmcnt(7)
; __device__ __forceinline__ float bf2f(bf16_t v) { return __uint_as_float(((unsigned)v) << 16); }
; __device__ __forceinline__ void s5_pass2_item(PP p, unsigned char* shm, int item, int l) {
;     ...
;         for (int t = 0; t < 16; ++t) { s5_rec(q, *(const f32x2*)(buL + (t * 64 + lane) * 2), x); xs[t * 132 + lane] = x.x; xs[t * 132 + 64 + lane] = x.y; }
;         __syncthreads();
;         f32x4 y0 = (f32x4){0.f, 0.f, 0.f, 0.f}, y1 = y0;
;         const f32x4* xrow = (const f32x4*)(xs + cc * 132 + quad * 32);
; #pragma unroll
;         for (int i = 0; i < 8; ++i) { const f32x4 xv = xrow[i];
;             y0 = __builtin_amdgcn_mfma_f32_16x16x4f32(xv[0], cmr[4 * i + 0], y0, 0, 0, 0);
;             y1 = __builtin_amdgcn_mfma_f32_16x16x4f32(xv[1], cmr[4 * i + 1], y1, 0, 0, 0);
;             y0 = __builtin_amdgcn_mfma_f32_16x16x4f32(xv[2], cmr[4 * i + 2], y0, 0, 0, 0);
;             y1 = __builtin_amdgcn_mfma_f32_16x16x4f32(xv[3], cmr[4 * i + 3], y1, 0, 0, 0); }
;     ...
;             const float v = y[r] + dsk * bf2f(proj[PJ_UA + (row0 + tl) * 512 + g * 16 + cc]);
	v_pk_add_f32 v[46:47], v[148:149], v[46:47]
	v_add_u32_e32 v80, 64, v98
	ds_write2st64_b32 v80, v46, v47 offset0:8 offset1:9
	v_xor_b32_e32 v52, 0x80000000, v47
	v_mov_b32_e32 v53, v46
	v_pk_mul_f32 v[52:53], v[0:1], v[52:53] op_sel_hi:[0,1]
	v_pk_fma_f32 v[46:47], v[84:85], v[46:47], v[52:53] op_sel_hi:[0,1,1]
	s_waitcnt lgkmcnt(7)
	v_pk_add_f32 v[46:47], v[150:151], v[46:47]
	v_add_u32_e32 v81, 0x50, v98
	ds_write2st64_b32 v81, v46, v47 offset0:10 offset1:11
	v_xor_b32_e32 v52, 0x80000000, v47
	v_mov_b32_e32 v53, v46
	v_pk_mul_f32 v[52:53], v[0:1], v[52:53] op_sel_hi:[0,1]
	v_pk_fma_f32 v[46:47], v[84:85], v[46:47], v[52:53] op_sel_hi:[0,1,1]
	s_waitcnt lgkmcnt(7)
	v_pk_add_f32 v[46:47], v[152:153], v[46:47]
	v_add_u32_e32 v86, 0x60, v98
	ds_write2st64_b32 v86, v46, v47 offset0:12 offset1:13
	v_xor_b32_e32 v52, 0x80000000, v47
	v_mov_b32_e32 v53, v46
	v_pk_mul_f32 v[52:53], v[0:1], v[52:53] op_sel_hi:[0,1]
	v_pk_fma_f32 v[46:47], v[84:85], v[46:47], v[52:53] op_sel_hi:[0,1,1]
	s_waitcnt lgkmcnt(7)
	v_pk_add_f32 v[46:47], v[154:155], v[46:47]
	v_add_u32_e32 v87, 0x70, v98
	ds_write2st64_b32 v87, v46, v47 offset0:14 offset1:15
	ds_read_b64 v[140:141], v90 offset:8192
	ds_read_b64 v[142:143], v90 offset:8704
	ds_read_b64 v[144:145], v90 offset:9216
	ds_read_b64 v[146:147], v90 offset:9728
	ds_read_b64 v[148:149], v90 offset:10240
	ds_read_b64 v[150:151], v90 offset:10752
	ds_read_b64 v[152:153], v90 offset:11264
	ds_read_b64 v[154:155], v90 offset:11776
	v_xor_b32_e32 v52, 0x80000000, v47
	v_mov_b32_e32 v53, v46
	v_pk_mul_f32 v[52:53], v[0:1], v[52:53] op_sel_hi:[0,1]
	v_pk_fma_f32 v[46:47], v[84:85], v[46:47], v[52:53] op_sel_hi:[0,1,1]
	s_waitcnt lgkmcnt(7)
	v_pk_add_f32 v[46:47], v[140:141], v[46:47]
	ds_write2st64_b32 v100, v46, v47 offset0:16 offset1:17
	v_xor_b32_e32 v52, 0x80000000, v47
	v_mov_b32_e32 v53, v46
	v_pk_mul_f32 v[52:53], v[0:1], v[52:53] op_sel_hi:[0,1]
	v_pk_fma_f32 v[46:47], v[84:85], v[46:47], v[52:53] op_sel_hi:[0,1,1]
	s_waitcnt lgkmcnt(7)
	v_pk_add_f32 v[46:47], v[142:143], v[46:47]
	ds_write2st64_b32 v101, v46, v47 offset0:18 offset1:19
	v_xor_b32_e32 v52, 0x80000000, v47
	v_mov_b32_e32 v53, v46
	v_pk_mul_f32 v[52:53], v[0:1], v[52:53] op_sel_hi:[0,1]
	v_pk_fma_f32 v[46:47], v[84:85], v[46:47], v[52:53] op_sel_hi:[0,1,1]
	s_waitcnt lgkmcnt(7)
	v_pk_add_f32 v[46:47], v[144:145], v[46:47]
	v_add_u32_e32 v102, 0xa0, v98
	ds_write2st64_b32 v102, v46, v47 offset0:20 offset1:21
	v_xor_b32_e32 v52, 0x80000000, v47
	v_mov_b32_e32 v53, v46
	v_pk_mul_f32 v[52:53], v[0:1], v[52:53] op_sel_hi:[0,1]
	v_pk_fma_f32 v[46:47], v[84:85], v[46:47], v[52:53] op_sel_hi:[0,1,1]
	s_waitcnt lgkmcnt(7)
	v_pk_add_f32 v[46:47], v[146:147], v[46:47]
	v_add_u32_e32 v103, 0xb0, v98
	ds_write2st64_b32 v103, v46, v47 offset0:22 offset1:23
	v_xor_b32_e32 v52, 0x80000000, v47
	v_mov_b32_e32 v53, v46
	v_pk_mul_f32 v[52:53], v[0:1], v[52:53] op_sel_hi:[0,1]
	v_pk_fma_f32 v[46:47], v[84:85], v[46:47], v[52:53] op_sel_hi:[0,1,1]
	s_waitcnt lgkmcnt(7)
	v_pk_add_f32 v[46:47], v[148:149], v[46:47]
	v_add_u32_e32 v104, 0xc0, v98
	ds_write2st64_b32 v104, v46, v47 offset0:24 offset1:25
	v_xor_b32_e32 v52, 0x80000000, v47
	v_mov_b32_e32 v53, v46
	v_pk_mul_f32 v[52:53], v[0:1], v[52:53] op_sel_hi:[0,1]
	v_pk_fma_f32 v[46:47], v[84:85], v[46:47], v[52:53] op_sel_hi:[0,1,1]
	s_waitcnt lgkmcnt(7)
	v_pk_add_f32 v[46:47], v[150:151], v[46:47]
	v_add_u32_e32 v105, 0xd0, v98
	ds_write2st64_b32 v105, v46, v47 offset0:26 offset1:27
	v_xor_b32_e32 v52, 0x80000000, v47
	v_mov_b32_e32 v53, v46
	v_pk_mul_f32 v[52:53], v[0:1], v[52:53] op_sel_hi:[0,1]
	v_pk_fma_f32 v[46:47], v[84:85], v[46:47], v[52:53] op_sel_hi:[0,1,1]
	s_waitcnt lgkmcnt(7)
	v_pk_add_f32 v[46:47], v[152:153], v[46:47]
	v_add_u32_e32 v106, 0xe0, v98
	ds_write2st64_b32 v106, v46, v47 offset0:28 offset1:29
	v_xor_b32_e32 v52, 0x80000000, v47
	v_mov_b32_e32 v53, v46
	v_pk_mul_f32 v[52:53], v[0:1], v[52:53] op_sel_hi:[0,1]
	v_pk_fma_f32 v[46:47], v[84:85], v[46:47], v[52:53] op_sel_hi:[0,1,1]
	s_waitcnt lgkmcnt(7)
	v_pk_add_f32 v[52:53], v[154:155], v[46:47]
	v_add_u32_e32 v107, 0xf0, v98
	ds_write2st64_b32 v107, v52, v53 offset0:30 offset1:31
	s_waitcnt lgkmcnt(0)
	s_barrier
	v_mov_b32_e32 v216, v82
	v_mov_b32_e32 v217, v83
	v_lshlrev_b64 v[216:217], 9, v[216:217]
	v_lshl_add_u64 v[216:217], v[216:217], 0, v[50:51]
	v_lshlrev_b64 v[216:217], 1, v[216:217]
	v_lshl_add_u64 v[216:217], s[8:9], 0, v[216:217]
	global_load_ushort v200, v[216:217], off
	global_load_ushort v201, v[216:217], off offset:1024
	global_load_ushort v202, v[216:217], off offset:2048
	global_load_ushort v203, v[216:217], off offset:3072
	ds_read_b128 v[46:49], v89
	ds_read_b128 v[110:113], v89 offset:16
	ds_read_b128 v[114:117], v89 offset:32
	ds_read_b128 v[118:121], v89 offset:48
	s_waitcnt lgkmcnt(3)
	v_mfma_f32_16x16x4_f32 v[122:125], v46, v97, 0
	v_mfma_f32_16x16x4_f32 v[126:129], v47, v96, 0
	v_mfma_f32_16x16x4_f32 v[122:125], v48, v95, v[122:125]
	v_mfma_f32_16x16x4_f32 v[46:49], v49, v94, v[126:129]
	s_waitcnt lgkmcnt(2)
	v_mfma_f32_16x16x4_f32 v[122:125], v110, v93, v[122:125]
	v_mfma_f32_16x16x4_f32 v[46:49], v111, v92, v[46:49]
	v_mfma_f32_16x16x4_f32 v[122:125], v112, v91, v[122:125]
	v_mfma_f32_16x16x4_f32 v[46:49], v113, v88, v[46:49]
	s_waitcnt lgkmcnt(1)
	v_mfma_f32_16x16x4_f32 v[110:113], v114, v85, v[122:125]
	v_mfma_f32_16x16x4_f32 v[46:49], v115, v55, v[46:49]
	v_mfma_f32_16x16x4_f32 v[110:113], v116, v56, v[110:113]
	v_mfma_f32_16x16x4_f32 v[46:49], v117, v57, v[46:49]
	ds_read_b128 v[114:117], v89 offset:64
	s_waitcnt lgkmcnt(1)
; __device__ __forceinline__ float bf2f(bf16_t v) { return __uint_as_float(((unsigned)v) << 16); }
; __device__ __forceinline__ bf16_t f2bf(float f) { unsigned u = __float_as_uint(f); u += 0x7FFFu + ((u >> 16) & 1u); return (bf16_t)(u >> 16); }
; __device__ __forceinline__ void s5_pass2_item(PP p, unsigned char* shm, int item, int l) {
;     ...
;         f32x4 y0 = (f32x4){0.f, 0.f, 0.f, 0.f}, y1 = y0;
;         const f32x4* xrow = (const f32x4*)(xs + cc * 132 + quad * 32);
; #pragma unroll
;         for (int i = 0; i < 8; ++i) { const f32x4 xv = xrow[i];
;             y0 = __builtin_amdgcn_mfma_f32_16x16x4f32(xv[0], cmr[4 * i + 0], y0, 0, 0, 0);
;             y1 = __builtin_amdgcn_mfma_f32_16x16x4f32(xv[1], cmr[4 * i + 1], y1, 0, 0, 0);
;             y0 = __builtin_amdgcn_mfma_f32_16x16x4f32(xv[2], cmr[4 * i + 2], y0, 0, 0, 0);
;             y1 = __builtin_amdgcn_mfma_f32_16x16x4f32(xv[3], cmr[4 * i + 3], y1, 0, 0, 0); }
;         const f32x4 y = y0 + y1;
; #pragma unroll
;         for (int r = 0; r < 4; ++r) { const int tl = sc * 16 + quad * 4 + r;
;             const float v = y[r] + dsk * bf2f(proj[PJ_UA + (row0 + tl) * 512 + g * 16 + cc]);
;             const float z = 0.7978845608028654f * (v + 0.044715f * v * v * v);
;             const float th = 1.0f - 2.0f / (__expf(2.0f * z) + 1.0f);
;             Gout[(row0 + tl) * 512 + g * 16 + cc] = f2bf(0.5f * v * (1.0f + th)); }
	v_mfma_f32_16x16x4_f32 v[110:113], v118, v58, v[110:113]
	v_mfma_f32_16x16x4_f32 v[46:49], v119, v59, v[46:49]
	v_mfma_f32_16x16x4_f32 v[110:113], v120, v60, v[110:113]
	v_mfma_f32_16x16x4_f32 v[46:49], v121, v61, v[46:49]
	s_waitcnt lgkmcnt(0)
	v_mfma_f32_16x16x4_f32 v[110:113], v114, v62, v[110:113]
	v_mfma_f32_16x16x4_f32 v[46:49], v115, v63, v[46:49]
	v_mfma_f32_16x16x4_f32 v[110:113], v116, v64, v[110:113]
	v_mfma_f32_16x16x4_f32 v[46:49], v117, v65, v[46:49]
	ds_read_b128 v[114:117], v89 offset:80
	s_waitcnt lgkmcnt(0)
	v_mfma_f32_16x16x4_f32 v[110:113], v114, v66, v[110:113]
	v_mfma_f32_16x16x4_f32 v[46:49], v115, v67, v[46:49]
	v_mfma_f32_16x16x4_f32 v[110:113], v116, v68, v[110:113]
	v_mfma_f32_16x16x4_f32 v[46:49], v117, v69, v[46:49]
	ds_read_b128 v[114:117], v89 offset:96
	s_waitcnt lgkmcnt(0)
	v_mfma_f32_16x16x4_f32 v[110:113], v114, v70, v[110:113]
	v_mfma_f32_16x16x4_f32 v[46:49], v115, v71, v[46:49]
	v_mfma_f32_16x16x4_f32 v[110:113], v116, v72, v[110:113]
	v_mfma_f32_16x16x4_f32 v[46:49], v117, v73, v[46:49]
	ds_read_b128 v[114:117], v89 offset:112
	s_waitcnt lgkmcnt(0)
	v_mfma_f32_16x16x4_f32 v[110:113], v114, v74, v[110:113]
	v_mfma_f32_16x16x4_f32 v[46:49], v115, v75, v[46:49]
	v_mfma_f32_16x16x4_f32 v[110:113], v116, v76, v[110:113]
	v_mfma_f32_16x16x4_f32 v[46:49], v117, v77, v[46:49]
	s_nop 9
	v_pk_add_f32 v[46:47], v[110:111], v[46:47]
	v_lshlrev_b64 v[110:111], 9, v[82:83]
	v_lshl_add_u64 v[110:111], v[110:111], 0, v[50:51]
	v_lshlrev_b64 v[110:111], 1, v[110:111]
	v_pk_add_f32 v[48:49], v[112:113], v[48:49]
	v_lshl_add_u64 v[112:113], s[8:9], 0, v[110:111]
	v_lshl_add_u64 v[110:111], s[28:29], 0, v[110:111]
	s_waitcnt vmcnt(3)
	v_lshlrev_b32_e32 v109, 16, v200
	v_fma_f32 v46, v54, v109, v46
	v_mul_f32_e32 v109, 0x3d372713, v46
	v_mul_f32_e32 v109, v46, v109
	v_fma_f32 v109, v46, v109, v46
	v_mul_f32_e32 v109, 0x3f4c422a, v109
	v_add_f32_e32 v109, v109, v109
	v_mul_f32_e32 v109, 0x3fb8aa3b, v109
	v_exp_f32_e32 v109, v109
	v_mul_f32_e32 v46, 0.5, v46
	v_add_f32_e32 v109, 1.0, v109
	v_div_scale_f32 v112, s[2:3], v109, v109, 2.0
	v_rcp_f32_e32 v113, v112
	s_nop 0
	v_fma_f32 v114, -v112, v113, 1.0
	v_fmac_f32_e32 v113, v114, v113
	v_div_scale_f32 v114, vcc, 2.0, v109, 2.0
	v_mul_f32_e32 v115, v114, v113
	v_fma_f32 v116, -v112, v115, v114
	v_fmac_f32_e32 v115, v116, v113
	v_fma_f32 v112, -v112, v115, v114
	v_div_fmas_f32 v112, v112, v113, v115
	v_div_fixup_f32 v109, v112, v109, 2.0
	v_sub_f32_e32 v109, 1.0, v109
	v_add_f32_e32 v109, 1.0, v109
	v_mul_f32_e32 v46, v46, v109
	v_bfe_u32 v109, v46, 16, 1
	v_add3_u32 v46, v46, v109, s31
	global_store_short_d16_hi v[110:111], v46, off
	v_or_b32_e32 v110, 1, v82
	v_mov_b32_e32 v111, v83
	v_lshlrev_b64 v[110:111], 9, v[110:111]
	v_lshl_add_u64 v[110:111], v[110:111], 0, v[50:51]
	v_lshlrev_b64 v[110:111], 1, v[110:111]
	v_lshl_add_u64 v[112:113], s[8:9], 0, v[110:111]
	s_waitcnt vmcnt(3)
	v_lshlrev_b32_e32 v46, 16, v201
	v_fmac_f32_e32 v47, v54, v46
	v_mul_f32_e32 v46, 0x3d372713, v47
	v_mul_f32_e32 v46, v47, v46
	v_fma_f32 v46, v47, v46, v47
	v_mul_f32_e32 v46, 0x3f4c422a, v46
	v_add_f32_e32 v46, v46, v46
	v_mul_f32_e32 v46, 0x3fb8aa3b, v46
	v_exp_f32_e32 v46, v46
	v_mul_f32_e32 v47, 0.5, v47
	v_add_f32_e32 v46, 1.0, v46
	v_div_scale_f32 v109, s[2:3], v46, v46, 2.0
	v_rcp_f32_e32 v112, v109
	s_nop 0
	v_fma_f32 v113, -v109, v112, 1.0
	v_fmac_f32_e32 v112, v113, v112
	v_div_scale_f32 v113, vcc, 2.0, v46, 2.0
	v_mul_f32_e32 v114, v113, v112
	v_fma_f32 v115, -v109, v114, v113
	v_fmac_f32_e32 v114, v115, v112
	v_fma_f32 v109, -v109, v114, v113
	v_div_fmas_f32 v109, v109, v112, v114
	v_div_fixup_f32 v46, v109, v46, 2.0
	v_sub_f32_e32 v46, 1.0, v46
	v_add_f32_e32 v46, 1.0, v46
	v_mul_f32_e32 v46, v47, v46
	v_bfe_u32 v47, v46, 16, 1
	v_add3_u32 v109, v46, v47, s31
	v_lshl_add_u64 v[46:47], s[28:29], 0, v[110:111]
	global_store_short_d16_hi v[46:47], v109, off
	v_or_b32_e32 v46, 2, v82
	v_mov_b32_e32 v47, v83
	v_lshlrev_b64 v[46:47], 9, v[46:47]
	v_lshl_add_u64 v[46:47], v[46:47], 0, v[50:51]
	v_lshlrev_b64 v[46:47], 1, v[46:47]
	v_lshl_add_u64 v[110:111], s[8:9], 0, v[46:47]
	v_lshl_add_u64 v[46:47], s[28:29], 0, v[46:47]
	s_waitcnt vmcnt(3)
	v_lshlrev_b32_e32 v109, 16, v202
	v_fma_f32 v48, v54, v109, v48
	v_mul_f32_e32 v109, 0x3d372713, v48
	v_mul_f32_e32 v109, v48, v109
	v_fma_f32 v109, v48, v109, v48
	v_mul_f32_e32 v109, 0x3f4c422a, v109
	v_add_f32_e32 v109, v109, v109
	v_mul_f32_e32 v109, 0x3fb8aa3b, v109
	v_exp_f32_e32 v109, v109
	v_mul_f32_e32 v48, 0.5, v48
	v_add_f32_e32 v109, 1.0, v109
	v_div_scale_f32 v110, s[2:3], v109, v109, 2.0
	v_rcp_f32_e32 v111, v110
	s_nop 0
	v_fma_f32 v112, -v110, v111, 1.0
	v_fmac_f32_e32 v111, v112, v111
	v_div_scale_f32 v112, vcc, 2.0, v109, 2.0
	v_mul_f32_e32 v113, v112, v111
	v_fma_f32 v114, -v110, v113, v112
	v_fmac_f32_e32 v113, v114, v111
	v_fma_f32 v110, -v110, v113, v112
	v_div_fmas_f32 v110, v110, v111, v113
	v_div_fixup_f32 v109, v110, v109, 2.0
	v_sub_f32_e32 v109, 1.0, v109
	v_add_f32_e32 v109, 1.0, v109
	v_mul_f32_e32 v48, v48, v109
	v_bfe_u32 v109, v48, 16, 1
	v_add3_u32 v48, v48, v109, s31
	global_store_short_d16_hi v[46:47], v48, off
	v_or_b32_e32 v46, 3, v82
	v_mov_b32_e32 v47, v83
	v_lshlrev_b64 v[46:47], 9, v[46:47]
	v_lshl_add_u64 v[46:47], v[46:47], 0, v[50:51]
	v_lshlrev_b64 v[46:47], 1, v[46:47]
	v_lshl_add_u64 v[110:111], s[8:9], 0, v[46:47]
	v_lshl_add_u64 v[46:47], s[28:29], 0, v[46:47]
	v_mfma_f32_16x16x32_bf16 v[114:117], v[42:45], v[30:33], 0
	s_waitcnt vmcnt(3)
	v_lshlrev_b32_e32 v48, 16, v203
	v_fmac_f32_e32 v49, v54, v48
	v_mul_f32_e32 v48, 0x3d372713, v49
	v_mul_f32_e32 v48, v49, v48
	v_fma_f32 v48, v49, v48, v49
	v_mul_f32_e32 v48, 0x3f4c422a, v48
	v_add_f32_e32 v48, v48, v48
	v_mul_f32_e32 v48, 0x3fb8aa3b, v48
	v_exp_f32_e32 v48, v48
	v_mul_f32_e32 v49, 0.5, v49
	v_mov_b32_e32 v123, v114
	v_add_f32_e32 v48, 1.0, v48
	v_div_scale_f32 v109, s[2:3], v48, v48, 2.0
	v_rcp_f32_e32 v110, v109
	s_nop 0
	v_fma_f32 v111, -v109, v110, 1.0
	v_fmac_f32_e32 v110, v111, v110
	v_div_scale_f32 v111, vcc, 2.0, v48, 2.0
	v_mul_f32_e32 v112, v111, v110
	v_fma_f32 v113, -v109, v112, v111
	v_fmac_f32_e32 v112, v113, v110
	v_fma_f32 v109, -v109, v112, v111
	v_div_fmas_f32 v109, v109, v110, v112
	v_div_fixup_f32 v48, v109, v48, 2.0
	v_sub_f32_e32 v48, 1.0, v48
	v_add_f32_e32 v48, 1.0, v48
	v_mul_f32_e32 v48, v49, v48
	v_bfe_u32 v49, v48, 16, 1
	v_add3_u32 v48, v48, v49, s31
	global_store_short_d16_hi v[46:47], v48, off
	v_mfma_f32_16x16x32_bf16 v[46:49], v[42:45], v[26:29], 0
	s_barrier
; __device__ __forceinline__ void s5_bu16(const S5Frag& f, const bf16x8 uf, float* buL, int lane) {
;     const int jj = lane & 15, quad = lane >> 4;
; #pragma unroll
;     for (int nt = 0; nt < 4; ++nt) {
;         const f32x4 z = (f32x4){0.f, 0.f, 0.f, 0.f};
;         const f32x4 dre = __builtin_amdgcn_mfma_f32_16x16x32_bf16(uf, f.bfr[nt], z, 0, 0, 0);
;         const f32x4 dim = __builtin_amdgcn_mfma_f32_16x16x32_bf16(uf, f.bfr[nt + 4], z, 0, 0, 0);
; #pragma unroll
;         for (int r = 0; r < 4; ++r) *(f32x2*)(buL + ((4 * quad + r) * 64 + 16 * nt + jj) * 2) = (f32x2){dre[r], dim[r]};
;     }
; __device__ __forceinline__ void s5_pass2_item(PP p, unsigned char* shm, int item, int l) {
;     ...
;     for (int sc = 0; sc < 4; ++sc) {
;         s5_bu16(f, uf[sc], buL, lane);
;         __syncthreads();
; #pragma unroll
;         for (int t = 0; t < 16; ++t) { s5_rec(q, *(const f32x2*)(buL + (t * 64 + lane) * 2), x); xs[t * 132 + lane] = x.x; xs[t * 132 + 64 + lane] = x.y; }
	v_mfma_f32_16x16x32_bf16 v[110:113], v[42:45], v[34:37], 0
	s_nop 5
	v_mov_b32_e32 v118, v46
	s_nop 0
	v_mov_b32_e32 v119, v110
	v_mov_b32_e32 v110, v47
	v_mov_b32_e32 v120, v48
	v_mov_b32_e32 v121, v112
	v_mov_b32_e32 v112, v49
	v_mfma_f32_16x16x32_bf16 v[46:49], v[42:45], v[22:25], 0
	s_nop 7
	v_mov_b32_e32 v122, v46
	v_mov_b32_e32 v114, v47
	v_mov_b32_e32 v46, v48
	v_mov_b32_e32 v47, v116
	ds_write2_b64 v108, v[118:119], v[122:123] offset1:16
	ds_write2_b64 v108, v[120:121], v[46:47] offset0:128 offset1:144
	v_mov_b32_e32 v116, v49
	v_mfma_f32_16x16x32_bf16 v[46:49], v[42:45], v[18:21], 0
	v_mfma_f32_16x16x32_bf16 v[118:121], v[42:45], v[14:17], 0
	s_nop 6
	v_mov_b32_e32 v122, v46
	v_mov_b32_e32 v123, v118
	v_mov_b32_e32 v118, v47
	v_mov_b32_e32 v46, v48
	v_mov_b32_e32 v47, v120
	ds_write2_b64 v108, v[46:47], v[112:113] offset0:160 offset1:192
	v_mov_b32_e32 v120, v49
	v_mfma_f32_16x16x32_bf16 v[46:49], v[42:45], v[10:13], 0
	ds_write2_b64 v108, v[122:123], v[110:111] offset0:32 offset1:64
	ds_write2_b64 v108, v[114:115], v[118:119] offset0:80 offset1:96
	ds_write2_b64 v108, v[116:117], v[120:121] offset0:208 offset1:224
	v_mfma_f32_16x16x32_bf16 v[42:45], v[42:45], v[6:9], 0
	s_nop 3
	v_mov_b32_e32 v110, v46
	s_nop 2
	v_mov_b32_e32 v111, v42
	v_mov_b32_e32 v42, v47
	ds_write2st64_b64 v99, v[110:111], v[42:43] offset0:8 offset1:9
	v_mov_b32_e32 v42, v48
	v_mov_b32_e32 v43, v44
	v_mov_b32_e32 v44, v49
	ds_write2st64_b64 v99, v[42:43], v[44:45] offset0:10 offset1:11
	s_waitcnt lgkmcnt(0)
	s_barrier
	ds_read_b64 v[140:141], v90 offset:4096
	ds_read_b64 v[142:143], v90 offset:4608
	ds_read_b64 v[144:145], v90 offset:5120
	ds_read_b64 v[146:147], v90 offset:5632
	ds_read_b64 v[148:149], v90 offset:6144
	ds_read_b64 v[150:151], v90 offset:6656
	ds_read_b64 v[152:153], v90 offset:7168
	ds_read_b64 v[154:155], v90 offset:7680
	v_xor_b32_e32 v44, 0x80000000, v53
	v_mov_b32_e32 v45, v52
	v_pk_mul_f32 v[44:45], v[0:1], v[44:45] op_sel_hi:[0,1]
	v_pk_fma_f32 v[44:45], v[84:85], v[52:53], v[44:45] op_sel_hi:[0,1,1]
	s_waitcnt lgkmcnt(7)
	v_pk_add_f32 v[42:43], v[44:45], v[140:141]
	ds_write2st64_b32 v98, v42, v43 offset1:1
	v_xor_b32_e32 v46, 0x80000000, v43
	v_mov_b32_e32 v47, v42
	v_pk_mul_f32 v[46:47], v[0:1], v[46:47] op_sel_hi:[0,1]
	v_pk_fma_f32 v[42:43], v[84:85], v[42:43], v[46:47] op_sel_hi:[0,1,1]
	s_waitcnt lgkmcnt(7)
	v_pk_add_f32 v[42:43], v[142:143], v[42:43]
	ds_write2_b32 v98, v42, v43 offset0:132 offset1:196
	v_xor_b32_e32 v46, 0x80000000, v43
	v_mov_b32_e32 v47, v42
	v_pk_mul_f32 v[46:47], v[0:1], v[46:47] op_sel_hi:[0,1]
	v_pk_fma_f32 v[42:43], v[84:85], v[42:43], v[46:47] op_sel_hi:[0,1,1]
	s_waitcnt lgkmcnt(7)
	v_pk_add_f32 v[42:43], v[144:145], v[42:43]
	ds_write2st64_b32 v78, v42, v43 offset0:4 offset1:5
	v_xor_b32_e32 v46, 0x80000000, v43
	v_mov_b32_e32 v47, v42
	v_pk_mul_f32 v[46:47], v[0:1], v[46:47] op_sel_hi:[0,1]
	v_pk_fma_f32 v[42:43], v[84:85], v[42:43], v[46:47] op_sel_hi:[0,1,1]
	s_waitcnt lgkmcnt(7)
	v_pk_add_f32 v[42:43], v[146:147], v[42:43]
	ds_write2st64_b32 v79, v42, v43 offset0:6 offset1:7
	v_xor_b32_e32 v46, 0x80000000, v43
	v_mov_b32_e32 v47, v42
	v_pk_mul_f32 v[46:47], v[0:1], v[46:47] op_sel_hi:[0,1]
	v_pk_fma_f32 v[42:43], v[84:85], v[42:43], v[46:47] op_sel_hi:[0,1,1]
	s_waitcnt lgkmcnt(7)
	v_pk_add_f32 v[42:43], v[148:149], v[42:43]
	ds_write2st64_b32 v80, v42, v43 offset0:8 offset1:9
	v_xor_b32_e32 v46, 0x80000000, v43
	v_mov_b32_e32 v47, v42
	v_pk_mul_f32 v[46:47], v[0:1], v[46:47] op_sel_hi:[0,1]
	v_pk_fma_f32 v[42:43], v[84:85], v[42:43], v[46:47] op_sel_hi:[0,1,1]
	s_waitcnt lgkmcnt(7)
	v_pk_add_f32 v[42:43], v[150:151], v[42:43]
	ds_write2st64_b32 v81, v42, v43 offset0:10 offset1:11
	v_xor_b32_e32 v46, 0x80000000, v43
	v_mov_b32_e32 v47, v42
	v_pk_mul_f32 v[46:47], v[0:1], v[46:47] op_sel_hi:[0,1]
	v_pk_fma_f32 v[42:43], v[84:85], v[42:43], v[46:47] op_sel_hi:[0,1,1]
	s_waitcnt lgkmcnt(7)
	v_pk_add_f32 v[42:43], v[152:153], v[42:43]
	ds_write2st64_b32 v86, v42, v43 offset0:12 offset1:13
	v_xor_b32_e32 v46, 0x80000000, v43
	v_mov_b32_e32 v47, v42
	v_pk_mul_f32 v[46:47], v[0:1], v[46:47] op_sel_hi:[0,1]
	v_pk_fma_f32 v[42:43], v[84:85], v[42:43], v[46:47] op_sel_hi:[0,1,1]
	s_waitcnt lgkmcnt(7)
	v_pk_add_f32 v[42:43], v[154:155], v[42:43]
	ds_write2st64_b32 v87, v42, v43 offset0:14 offset1:15
	ds_read_b64 v[140:141], v90 offset:8192
	ds_read_b64 v[142:143], v90 offset:8704
	ds_read_b64 v[144:145], v90 offset:9216
	ds_read_b64 v[146:147], v90 offset:9728
	ds_read_b64 v[148:149], v90 offset:10240
	ds_read_b64 v[150:151], v90 offset:10752
	ds_read_b64 v[152:153], v90 offset:11264
	ds_read_b64 v[154:155], v90 offset:11776
	v_xor_b32_e32 v46, 0x80000000, v43
	v_mov_b32_e32 v47, v42
	v_pk_mul_f32 v[46:47], v[0:1], v[46:47] op_sel_hi:[0,1]
	v_pk_fma_f32 v[42:43], v[84:85], v[42:43], v[46:47] op_sel_hi:[0,1,1]
	s_waitcnt lgkmcnt(7)
	v_pk_add_f32 v[42:43], v[140:141], v[42:43]
	ds_write2st64_b32 v100, v42, v43 offset0:16 offset1:17
	v_xor_b32_e32 v46, 0x80000000, v43
	v_mov_b32_e32 v47, v42
	v_pk_mul_f32 v[46:47], v[0:1], v[46:47] op_sel_hi:[0,1]
	v_pk_fma_f32 v[42:43], v[84:85], v[42:43], v[46:47] op_sel_hi:[0,1,1]
	s_waitcnt lgkmcnt(7)
	v_pk_add_f32 v[42:43], v[142:143], v[42:43]
	ds_write2st64_b32 v101, v42, v43 offset0:18 offset1:19
	v_xor_b32_e32 v46, 0x80000000, v43
	v_mov_b32_e32 v47, v42
	v_pk_mul_f32 v[46:47], v[0:1], v[46:47] op_sel_hi:[0,1]
	v_pk_fma_f32 v[42:43], v[84:85], v[42:43], v[46:47] op_sel_hi:[0,1,1]
	s_waitcnt lgkmcnt(7)
	v_pk_add_f32 v[42:43], v[144:145], v[42:43]
	ds_write2st64_b32 v102, v42, v43 offset0:20 offset1:21
	v_xor_b32_e32 v46, 0x80000000, v43
	v_mov_b32_e32 v47, v42
	v_pk_mul_f32 v[46:47], v[0:1], v[46:47] op_sel_hi:[0,1]
	v_pk_fma_f32 v[42:43], v[84:85], v[42:43], v[46:47] op_sel_hi:[0,1,1]
	s_waitcnt lgkmcnt(7)
; __device__ __forceinline__ float bf2f(bf16_t v) { return __uint_as_float(((unsigned)v) << 16); }
; __device__ __forceinline__ bf16_t f2bf(float f) { unsigned u = __float_as_uint(f); u += 0x7FFFu + ((u >> 16) & 1u); return (bf16_t)(u >> 16); }
; __device__ __forceinline__ void s5_pass2_item(PP p, unsigned char* shm, int item, int l) {
;     ...
;         for (int t = 0; t < 16; ++t) { s5_rec(q, *(const f32x2*)(buL + (t * 64 + lane) * 2), x); xs[t * 132 + lane] = x.x; xs[t * 132 + 64 + lane] = x.y; }
;         __syncthreads();
;         f32x4 y0 = (f32x4){0.f, 0.f, 0.f, 0.f}, y1 = y0;
;         const f32x4* xrow = (const f32x4*)(xs + cc * 132 + quad * 32);
; #pragma unroll
;         for (int i = 0; i < 8; ++i) { const f32x4 xv = xrow[i];
;             y0 = __builtin_amdgcn_mfma_f32_16x16x4f32(xv[0], cmr[4 * i + 0], y0, 0, 0, 0);
;             y1 = __builtin_amdgcn_mfma_f32_16x16x4f32(xv[1], cmr[4 * i + 1], y1, 0, 0, 0);
;             y0 = __builtin_amdgcn_mfma_f32_16x16x4f32(xv[2], cmr[4 * i + 2], y0, 0, 0, 0);
;             y1 = __builtin_amdgcn_mfma_f32_16x16x4f32(xv[3], cmr[4 * i + 3], y1, 0, 0, 0); }
;         const f32x4 y = y0 + y1;
; #pragma unroll
;         for (int r = 0; r < 4; ++r) { const int tl = sc * 16 + quad * 4 + r;
;             const float v = y[r] + dsk * bf2f(proj[PJ_UA + (row0 + tl) * 512 + g * 16 + cc]);
;             const float z = 0.7978845608028654f * (v + 0.044715f * v * v * v);
;             const float th = 1.0f - 2.0f / (__expf(2.0f * z) + 1.0f);
;             Gout[(row0 + tl) * 512 + g * 16 + cc] = f2bf(0.5f * v * (1.0f + th)); }
	v_pk_add_f32 v[42:43], v[146:147], v[42:43]
	ds_write2st64_b32 v103, v42, v43 offset0:22 offset1:23
	v_xor_b32_e32 v46, 0x80000000, v43
	v_mov_b32_e32 v47, v42
	v_pk_mul_f32 v[46:47], v[0:1], v[46:47] op_sel_hi:[0,1]
	v_pk_fma_f32 v[42:43], v[84:85], v[42:43], v[46:47] op_sel_hi:[0,1,1]
	s_waitcnt lgkmcnt(7)
	v_pk_add_f32 v[42:43], v[148:149], v[42:43]
	ds_write2st64_b32 v104, v42, v43 offset0:24 offset1:25
	v_xor_b32_e32 v46, 0x80000000, v43
	v_mov_b32_e32 v47, v42
	v_pk_mul_f32 v[46:47], v[0:1], v[46:47] op_sel_hi:[0,1]
	v_pk_fma_f32 v[42:43], v[84:85], v[42:43], v[46:47] op_sel_hi:[0,1,1]
	s_waitcnt lgkmcnt(7)
	v_pk_add_f32 v[42:43], v[150:151], v[42:43]
	ds_write2st64_b32 v105, v42, v43 offset0:26 offset1:27
	v_xor_b32_e32 v46, 0x80000000, v43
	v_mov_b32_e32 v47, v42
	v_pk_mul_f32 v[46:47], v[0:1], v[46:47] op_sel_hi:[0,1]
	v_pk_fma_f32 v[42:43], v[84:85], v[42:43], v[46:47] op_sel_hi:[0,1,1]
	s_waitcnt lgkmcnt(7)
	v_pk_add_f32 v[42:43], v[152:153], v[42:43]
	ds_write2st64_b32 v106, v42, v43 offset0:28 offset1:29
	v_xor_b32_e32 v46, 0x80000000, v43
	v_mov_b32_e32 v47, v42
	v_pk_mul_f32 v[46:47], v[0:1], v[46:47] op_sel_hi:[0,1]
	v_pk_fma_f32 v[42:43], v[84:85], v[42:43], v[46:47] op_sel_hi:[0,1,1]
	s_waitcnt lgkmcnt(7)
	v_pk_add_f32 v[46:47], v[154:155], v[42:43]
	ds_write2st64_b32 v107, v46, v47 offset0:30 offset1:31
	s_waitcnt lgkmcnt(0)
	s_barrier
	v_or_b32_e32 v216, 16, v82
	v_mov_b32_e32 v217, v83
	v_lshlrev_b64 v[216:217], 9, v[216:217]
	v_lshl_add_u64 v[216:217], v[216:217], 0, v[50:51]
	v_lshlrev_b64 v[216:217], 1, v[216:217]
	v_lshl_add_u64 v[216:217], s[8:9], 0, v[216:217]
	global_load_ushort v204, v[216:217], off
	global_load_ushort v205, v[216:217], off offset:1024
	global_load_ushort v206, v[216:217], off offset:2048
	global_load_ushort v207, v[216:217], off offset:3072
	ds_read_b128 v[42:45], v89
	ds_read_b128 v[110:113], v89 offset:16
	ds_read_b128 v[114:117], v89 offset:32
	ds_read_b128 v[118:121], v89 offset:48
	s_waitcnt lgkmcnt(3)
	v_mfma_f32_16x16x4_f32 v[122:125], v42, v97, 0
	v_or_b32_e32 v48, 16, v82
	v_mov_b32_e32 v49, v83
	v_lshlrev_b64 v[48:49], 9, v[48:49]
	v_lshl_add_u64 v[48:49], v[48:49], 0, v[50:51]
	v_lshlrev_b64 v[48:49], 1, v[48:49]
	v_lshl_add_u64 v[52:53], s[8:9], 0, v[48:49]
	v_mfma_f32_16x16x4_f32 v[126:129], v43, v96, 0
	v_lshl_add_u64 v[48:49], s[28:29], 0, v[48:49]
	s_waitcnt vmcnt(3)
	v_lshlrev_b32_e32 v52, 16, v204
	v_mfma_f32_16x16x4_f32 v[122:125], v44, v95, v[122:125]
	v_mfma_f32_16x16x4_f32 v[42:45], v45, v94, v[126:129]
	s_waitcnt lgkmcnt(2)
	v_mfma_f32_16x16x4_f32 v[122:125], v110, v93, v[122:125]
	v_mfma_f32_16x16x4_f32 v[42:45], v111, v92, v[42:45]
	v_mfma_f32_16x16x4_f32 v[122:125], v112, v91, v[122:125]
	v_mfma_f32_16x16x4_f32 v[42:45], v113, v88, v[42:45]
	s_waitcnt lgkmcnt(1)
	v_mfma_f32_16x16x4_f32 v[110:113], v114, v85, v[122:125]
	v_mfma_f32_16x16x4_f32 v[42:45], v115, v55, v[42:45]
	v_mfma_f32_16x16x4_f32 v[110:113], v116, v56, v[110:113]
	v_mfma_f32_16x16x4_f32 v[42:45], v117, v57, v[42:45]
	ds_read_b128 v[114:117], v89 offset:64
	s_waitcnt lgkmcnt(1)
	v_mfma_f32_16x16x4_f32 v[110:113], v118, v58, v[110:113]
	v_mfma_f32_16x16x4_f32 v[42:45], v119, v59, v[42:45]
	v_mfma_f32_16x16x4_f32 v[110:113], v120, v60, v[110:113]
	v_mfma_f32_16x16x4_f32 v[42:45], v121, v61, v[42:45]
	s_waitcnt lgkmcnt(0)
	v_mfma_f32_16x16x4_f32 v[110:113], v114, v62, v[110:113]
	v_mfma_f32_16x16x4_f32 v[42:45], v115, v63, v[42:45]
	v_mfma_f32_16x16x4_f32 v[110:113], v116, v64, v[110:113]
	v_mfma_f32_16x16x4_f32 v[42:45], v117, v65, v[42:45]
	ds_read_b128 v[114:117], v89 offset:80
	s_waitcnt lgkmcnt(0)
	v_mfma_f32_16x16x4_f32 v[110:113], v114, v66, v[110:113]
	v_mfma_f32_16x16x4_f32 v[42:45], v115, v67, v[42:45]
	v_mfma_f32_16x16x4_f32 v[110:113], v116, v68, v[110:113]
	v_mfma_f32_16x16x4_f32 v[42:45], v117, v69, v[42:45]
	ds_read_b128 v[114:117], v89 offset:96
	s_waitcnt lgkmcnt(0)
	v_mfma_f32_16x16x4_f32 v[110:113], v114, v70, v[110:113]
	v_mfma_f32_16x16x4_f32 v[42:45], v115, v71, v[42:45]
	v_mfma_f32_16x16x4_f32 v[110:113], v116, v72, v[110:113]
	v_mfma_f32_16x16x4_f32 v[42:45], v117, v73, v[42:45]
	ds_read_b128 v[114:117], v89 offset:112
	s_waitcnt lgkmcnt(0)
	v_mfma_f32_16x16x4_f32 v[110:113], v114, v74, v[110:113]
	v_mfma_f32_16x16x4_f32 v[42:45], v115, v75, v[42:45]
	v_mfma_f32_16x16x4_f32 v[110:113], v116, v76, v[110:113]
	v_mfma_f32_16x16x4_f32 v[42:45], v117, v77, v[42:45]
	v_mfma_f32_16x16x32_bf16 v[114:117], v[38:41], v[30:33], 0
	s_nop 8
	v_add_f32_e64 v42, v110, v42
	v_add_f32_e64 v43, v111, v43
	v_pk_add_f32 v[44:45], v[112:113], v[44:45]
	v_fma_f32 v42, v54, v52, v42
	v_mul_f32_e32 v52, 0x3d372713, v42
	v_mul_f32_e32 v52, v42, v52
	v_fma_f32 v52, v42, v52, v42
	v_mul_f32_e32 v52, 0x3f4c422a, v52
	v_add_f32_e32 v52, v52, v52
	v_mul_f32_e32 v52, 0x3fb8aa3b, v52
	v_exp_f32_e32 v52, v52
	v_mul_f32_e32 v42, 0.5, v42
	v_mov_b32_e32 v119, v114
	v_mfma_f32_16x16x32_bf16 v[30:33], v[2:5], v[30:33], 0
	v_add_f32_e32 v52, 1.0, v52
	v_div_scale_f32 v53, s[2:3], v52, v52, 2.0
	v_rcp_f32_e32 v109, v53
	s_nop 0
	v_fma_f32 v110, -v53, v109, 1.0
	v_fmac_f32_e32 v109, v110, v109
	v_div_scale_f32 v110, vcc, 2.0, v52, 2.0
	v_mul_f32_e32 v111, v110, v109
	v_fma_f32 v112, -v53, v111, v110
	v_fmac_f32_e32 v111, v112, v109
	v_fma_f32 v53, -v53, v111, v110
	v_div_fmas_f32 v53, v53, v109, v111
	v_div_fixup_f32 v52, v53, v52, 2.0
	v_sub_f32_e32 v52, 1.0, v52
	v_add_f32_e32 v52, 1.0, v52
	v_mul_f32_e32 v42, v42, v52
	v_bfe_u32 v52, v42, 16, 1
	v_add3_u32 v42, v42, v52, s31
	global_store_short_d16_hi v[48:49], v42, off
	v_or_b32_e32 v48, 17, v82
	v_mov_b32_e32 v49, v83
	v_lshlrev_b64 v[48:49], 9, v[48:49]
	v_lshl_add_u64 v[48:49], v[48:49], 0, v[50:51]
	v_lshlrev_b64 v[48:49], 1, v[48:49]
	v_lshl_add_u64 v[52:53], s[8:9], 0, v[48:49]
	s_waitcnt vmcnt(3)
; __device__ __forceinline__ float bf2f(bf16_t v) { return __uint_as_float(((unsigned)v) << 16); }
; __device__ __forceinline__ bf16_t f2bf(float f) { unsigned u = __float_as_uint(f); u += 0x7FFFu + ((u >> 16) & 1u); return (bf16_t)(u >> 16); }
; __device__ __forceinline__ void s5_bu16(const S5Frag& f, const bf16x8 uf, float* buL, int lane) {
;     const int jj = lane & 15, quad = lane >> 4;
; #pragma unroll
;     for (int nt = 0; nt < 4; ++nt) {
;         const f32x4 z = (f32x4){0.f, 0.f, 0.f, 0.f};
;         const f32x4 dre = __builtin_amdgcn_mfma_f32_16x16x32_bf16(uf, f.bfr[nt], z, 0, 0, 0);
;         const f32x4 dim = __builtin_amdgcn_mfma_f32_16x16x32_bf16(uf, f.bfr[nt + 4], z, 0, 0, 0);
; #pragma unroll
;         for (int r = 0; r < 4; ++r) *(f32x2*)(buL + ((4 * quad + r) * 64 + 16 * nt + jj) * 2) = (f32x2){dre[r], dim[r]};
;     }
; __device__ __forceinline__ void s5_pass2_item(PP p, unsigned char* shm, int item, int l) {
;     ...
;         const f32x4 y = y0 + y1;
; #pragma unroll
;         for (int r = 0; r < 4; ++r) { const int tl = sc * 16 + quad * 4 + r;
;             const float v = y[r] + dsk * bf2f(proj[PJ_UA + (row0 + tl) * 512 + g * 16 + cc]);
;             const float z = 0.7978845608028654f * (v + 0.044715f * v * v * v);
;             const float th = 1.0f - 2.0f / (__expf(2.0f * z) + 1.0f);
;             Gout[(row0 + tl) * 512 + g * 16 + cc] = f2bf(0.5f * v * (1.0f + th)); }
	v_lshlrev_b32_e32 v42, 16, v205
	v_fmac_f32_e32 v43, v54, v42
	v_mul_f32_e32 v42, 0x3d372713, v43
	v_mul_f32_e32 v42, v43, v42
	v_fma_f32 v42, v43, v42, v43
	v_mul_f32_e32 v42, 0x3f4c422a, v42
	v_add_f32_e32 v42, v42, v42
	v_mul_f32_e32 v42, 0x3fb8aa3b, v42
	v_exp_f32_e32 v42, v42
	v_mul_f32_e32 v43, 0.5, v43
	v_add_f32_e32 v42, 1.0, v42
	v_div_scale_f32 v52, s[2:3], v42, v42, 2.0
	v_rcp_f32_e32 v53, v52
	s_nop 0
	v_fma_f32 v109, -v52, v53, 1.0
	v_fmac_f32_e32 v53, v109, v53
	v_div_scale_f32 v109, vcc, 2.0, v42, 2.0
	v_mul_f32_e32 v110, v109, v53
	v_fma_f32 v111, -v52, v110, v109
	v_fmac_f32_e32 v110, v111, v53
	v_fma_f32 v52, -v52, v110, v109
	v_div_fmas_f32 v52, v52, v53, v110
	v_div_fixup_f32 v42, v52, v42, 2.0
	v_sub_f32_e32 v42, 1.0, v42
	v_add_f32_e32 v42, 1.0, v42
	v_mul_f32_e32 v42, v43, v42
	v_bfe_u32 v43, v42, 16, 1
	v_add3_u32 v52, v42, v43, s31
	v_lshl_add_u64 v[42:43], s[28:29], 0, v[48:49]
	global_store_short_d16_hi v[42:43], v52, off
	v_or_b32_e32 v42, 18, v82
	v_mov_b32_e32 v43, v83
	v_lshlrev_b64 v[42:43], 9, v[42:43]
	v_lshl_add_u64 v[42:43], v[42:43], 0, v[50:51]
	v_lshlrev_b64 v[42:43], 1, v[42:43]
	v_lshl_add_u64 v[48:49], s[8:9], 0, v[42:43]
	v_lshl_add_u64 v[42:43], s[28:29], 0, v[42:43]
	s_waitcnt vmcnt(3)
	v_lshlrev_b32_e32 v48, 16, v206
	v_fma_f32 v44, v54, v48, v44
	v_mul_f32_e32 v48, 0x3d372713, v44
	v_mul_f32_e32 v48, v44, v48
	v_fma_f32 v48, v44, v48, v44
	v_mul_f32_e32 v48, 0x3f4c422a, v48
	v_add_f32_e32 v48, v48, v48
	v_mul_f32_e32 v48, 0x3fb8aa3b, v48
	v_exp_f32_e32 v48, v48
	v_mul_f32_e32 v44, 0.5, v44
	v_add_f32_e32 v48, 1.0, v48
	v_div_scale_f32 v49, s[2:3], v48, v48, 2.0
	v_rcp_f32_e32 v52, v49
	s_nop 0
	v_fma_f32 v53, -v49, v52, 1.0
	v_fmac_f32_e32 v52, v53, v52
	v_div_scale_f32 v53, vcc, 2.0, v48, 2.0
	v_mul_f32_e32 v109, v53, v52
	v_fma_f32 v110, -v49, v109, v53
	v_fmac_f32_e32 v109, v110, v52
	v_fma_f32 v49, -v49, v109, v53
	v_div_fmas_f32 v49, v49, v52, v109
	v_div_fixup_f32 v48, v49, v48, 2.0
	v_sub_f32_e32 v48, 1.0, v48
	v_add_f32_e32 v48, 1.0, v48
	v_mul_f32_e32 v44, v44, v48
	v_bfe_u32 v48, v44, 16, 1
	v_add3_u32 v44, v44, v48, s31
	global_store_short_d16_hi v[42:43], v44, off
	v_or_b32_e32 v42, 19, v82
	v_mov_b32_e32 v43, v83
	v_lshlrev_b64 v[42:43], 9, v[42:43]
	v_lshl_add_u64 v[42:43], v[42:43], 0, v[50:51]
	v_lshlrev_b64 v[42:43], 1, v[42:43]
	v_lshl_add_u64 v[48:49], s[8:9], 0, v[42:43]
	v_lshl_add_u64 v[42:43], s[28:29], 0, v[42:43]
	v_mfma_f32_16x16x32_bf16 v[110:113], v[38:41], v[26:29], 0
	s_waitcnt vmcnt(3)
	v_lshlrev_b32_e32 v44, 16, v207
	v_fmac_f32_e32 v45, v54, v44
	v_mul_f32_e32 v44, 0x3d372713, v45
	v_mul_f32_e32 v44, v45, v44
	v_fma_f32 v44, v45, v44, v45
	v_mul_f32_e32 v44, 0x3f4c422a, v44
	v_add_f32_e32 v44, v44, v44
	v_mul_f32_e32 v44, 0x3fb8aa3b, v44
	v_exp_f32_e32 v44, v44
	v_mul_f32_e32 v45, 0.5, v45
	v_add_f32_e32 v44, 1.0, v44
	v_div_scale_f32 v48, s[2:3], v44, v44, 2.0
	v_rcp_f32_e32 v49, v48
	s_nop 0
	v_fma_f32 v52, -v48, v49, 1.0
	v_fmac_f32_e32 v49, v52, v49
	v_div_scale_f32 v52, vcc, 2.0, v44, 2.0
	v_mul_f32_e32 v53, v52, v49
	v_fma_f32 v109, -v48, v53, v52
	v_fmac_f32_e32 v53, v109, v49
	v_fma_f32 v48, -v48, v53, v52
	v_div_fmas_f32 v48, v48, v49, v53
	v_div_fixup_f32 v44, v48, v44, 2.0
	v_sub_f32_e32 v44, 1.0, v44
	v_add_f32_e32 v44, 1.0, v44
	v_mul_f32_e32 v44, v45, v44
	v_bfe_u32 v45, v44, 16, 1
	v_add3_u32 v44, v44, v45, s31
	global_store_short_d16_hi v[42:43], v44, off
	v_mfma_f32_16x16x32_bf16 v[42:45], v[38:41], v[34:37], 0
	v_mov_b32_e32 v48, v110
	v_mov_b32_e32 v52, v112
	s_barrier
	s_nop 4
	v_mov_b32_e32 v49, v42
	v_mov_b32_e32 v42, v111
	v_mov_b32_e32 v53, v44
	v_mov_b32_e32 v44, v113
	v_mfma_f32_16x16x32_bf16 v[110:113], v[38:41], v[22:25], 0
	v_mfma_f32_16x16x32_bf16 v[22:25], v[2:5], v[22:25], 0
	s_nop 6
	v_mov_b32_e32 v118, v110
	ds_write2_b64 v108, v[48:49], v[118:119] offset1:16
	v_mov_b32_e32 v114, v111
	v_mov_b32_e32 v48, v112
	v_mov_b32_e32 v49, v116
	v_mov_b32_e32 v116, v113
	v_mfma_f32_16x16x32_bf16 v[110:113], v[38:41], v[18:21], 0
	ds_write2_b64 v108, v[52:53], v[48:49] offset0:128 offset1:144
	v_mfma_f32_16x16x32_bf16 v[118:121], v[38:41], v[14:17], 0
	v_mfma_f32_16x16x32_bf16 v[18:21], v[2:5], v[18:21], 0
	s_nop 4
	v_mov_b32_e32 v48, v110
	s_nop 0
	v_mov_b32_e32 v49, v118
	ds_write2_b64 v108, v[48:49], v[42:43] offset0:32 offset1:64
	v_mov_b32_e32 v42, v112
	v_mov_b32_e32 v43, v120
	ds_write2_b64 v108, v[42:43], v[44:45] offset0:160 offset1:192
	v_mfma_f32_16x16x32_bf16 v[42:45], v[38:41], v[10:13], 0
	v_mov_b32_e32 v118, v111
	v_mov_b32_e32 v120, v113
	ds_write2_b64 v108, v[114:115], v[118:119] offset0:80 offset1:96
	v_mfma_f32_16x16x32_bf16 v[38:41], v[38:41], v[6:9], 0
	ds_write2_b64 v108, v[116:117], v[120:121] offset0:208 offset1:224
	s_nop 2
	v_mov_b32_e32 v48, v42
	v_mfma_f32_16x16x32_bf16 v[14:17], v[2:5], v[14:17], 0
	v_mfma_f32_16x16x32_bf16 v[10:13], v[2:5], v[10:13], 0
	s_nop 0
	v_mov_b32_e32 v49, v38
	v_mov_b32_e32 v38, v43
	ds_write2st64_b64 v99, v[48:49], v[38:39] offset0:8 offset1:9
	v_mov_b32_e32 v38, v44
	v_mov_b32_e32 v39, v40
	v_mov_b32_e32 v40, v45
	ds_write2st64_b64 v99, v[38:39], v[40:41] offset0:10 offset1:11
	s_waitcnt lgkmcnt(0)
	s_barrier
; __device__ __forceinline__ void s5_pass2_item(PP p, unsigned char* shm, int item, int l) {
;     ...
;     for (int sc = 0; sc < 4; ++sc) {
;         s5_bu16(f, uf[sc], buL, lane);
;         __syncthreads();
; #pragma unroll
;         for (int t = 0; t < 16; ++t) { s5_rec(q, *(const f32x2*)(buL + (t * 64 + lane) * 2), x); xs[t * 132 + lane] = x.x; xs[t * 132 + 64 + lane] = x.y; }
	ds_read_b64 v[140:141], v90 offset:4096
	ds_read_b64 v[142:143], v90 offset:4608
	ds_read_b64 v[144:145], v90 offset:5120
	ds_read_b64 v[146:147], v90 offset:5632
	ds_read_b64 v[148:149], v90 offset:6144
	ds_read_b64 v[150:151], v90 offset:6656
	ds_read_b64 v[152:153], v90 offset:7168
	ds_read_b64 v[154:155], v90 offset:7680
	v_xor_b32_e32 v40, 0x80000000, v47
	v_mov_b32_e32 v41, v46
	v_pk_mul_f32 v[40:41], v[0:1], v[40:41] op_sel_hi:[0,1]
	v_pk_fma_f32 v[40:41], v[84:85], v[46:47], v[40:41] op_sel_hi:[0,1,1]
	s_waitcnt lgkmcnt(7)
	v_pk_add_f32 v[38:39], v[40:41], v[140:141]
	ds_write2st64_b32 v98, v38, v39 offset1:1
	v_xor_b32_e32 v42, 0x80000000, v39
	v_mov_b32_e32 v43, v38
	v_pk_mul_f32 v[42:43], v[0:1], v[42:43] op_sel_hi:[0,1]
	v_pk_fma_f32 v[38:39], v[84:85], v[38:39], v[42:43] op_sel_hi:[0,1,1]
	s_waitcnt lgkmcnt(7)
	v_pk_add_f32 v[38:39], v[142:143], v[38:39]
	ds_write2_b32 v98, v38, v39 offset0:132 offset1:196
	v_xor_b32_e32 v42, 0x80000000, v39
	v_mov_b32_e32 v43, v38
	v_pk_mul_f32 v[42:43], v[0:1], v[42:43] op_sel_hi:[0,1]
	v_pk_fma_f32 v[38:39], v[84:85], v[38:39], v[42:43] op_sel_hi:[0,1,1]
	s_waitcnt lgkmcnt(7)
	v_pk_add_f32 v[38:39], v[144:145], v[38:39]
	ds_write2st64_b32 v78, v38, v39 offset0:4 offset1:5
	v_xor_b32_e32 v42, 0x80000000, v39
	v_mov_b32_e32 v43, v38
	v_pk_mul_f32 v[42:43], v[0:1], v[42:43] op_sel_hi:[0,1]
	v_pk_fma_f32 v[38:39], v[84:85], v[38:39], v[42:43] op_sel_hi:[0,1,1]
	s_waitcnt lgkmcnt(7)
	v_pk_add_f32 v[38:39], v[146:147], v[38:39]
	ds_write2st64_b32 v79, v38, v39 offset0:6 offset1:7
	v_xor_b32_e32 v42, 0x80000000, v39
	v_mov_b32_e32 v43, v38
	v_pk_mul_f32 v[42:43], v[0:1], v[42:43] op_sel_hi:[0,1]
	v_pk_fma_f32 v[38:39], v[84:85], v[38:39], v[42:43] op_sel_hi:[0,1,1]
	s_waitcnt lgkmcnt(7)
	v_pk_add_f32 v[38:39], v[148:149], v[38:39]
	ds_write2st64_b32 v80, v38, v39 offset0:8 offset1:9
	v_xor_b32_e32 v42, 0x80000000, v39
	v_mov_b32_e32 v43, v38
	v_pk_mul_f32 v[42:43], v[0:1], v[42:43] op_sel_hi:[0,1]
	v_pk_fma_f32 v[38:39], v[84:85], v[38:39], v[42:43] op_sel_hi:[0,1,1]
	s_waitcnt lgkmcnt(7)
	v_pk_add_f32 v[38:39], v[150:151], v[38:39]
	ds_write2st64_b32 v81, v38, v39 offset0:10 offset1:11
	v_xor_b32_e32 v42, 0x80000000, v39
	v_mov_b32_e32 v43, v38
	v_pk_mul_f32 v[42:43], v[0:1], v[42:43] op_sel_hi:[0,1]
	v_pk_fma_f32 v[38:39], v[84:85], v[38:39], v[42:43] op_sel_hi:[0,1,1]
	s_waitcnt lgkmcnt(7)
	v_pk_add_f32 v[38:39], v[152:153], v[38:39]
	ds_write2st64_b32 v86, v38, v39 offset0:12 offset1:13
	v_xor_b32_e32 v42, 0x80000000, v39
	v_mov_b32_e32 v43, v38
	v_pk_mul_f32 v[42:43], v[0:1], v[42:43] op_sel_hi:[0,1]
	v_pk_fma_f32 v[38:39], v[84:85], v[38:39], v[42:43] op_sel_hi:[0,1,1]
	s_waitcnt lgkmcnt(7)
	v_pk_add_f32 v[38:39], v[154:155], v[38:39]
	ds_write2st64_b32 v87, v38, v39 offset0:14 offset1:15
	ds_read_b64 v[140:141], v90 offset:8192
	ds_read_b64 v[142:143], v90 offset:8704
	ds_read_b64 v[144:145], v90 offset:9216
	ds_read_b64 v[146:147], v90 offset:9728
	ds_read_b64 v[148:149], v90 offset:10240
	ds_read_b64 v[150:151], v90 offset:10752
	ds_read_b64 v[152:153], v90 offset:11264
	ds_read_b64 v[154:155], v90 offset:11776
	v_xor_b32_e32 v42, 0x80000000, v39
	v_mov_b32_e32 v43, v38
	v_pk_mul_f32 v[42:43], v[0:1], v[42:43] op_sel_hi:[0,1]
	v_pk_fma_f32 v[38:39], v[84:85], v[38:39], v[42:43] op_sel_hi:[0,1,1]
	s_waitcnt lgkmcnt(7)
	v_pk_add_f32 v[38:39], v[140:141], v[38:39]
	ds_write2st64_b32 v100, v38, v39 offset0:16 offset1:17
	v_xor_b32_e32 v42, 0x80000000, v39
	v_mov_b32_e32 v43, v38
	v_pk_mul_f32 v[42:43], v[0:1], v[42:43] op_sel_hi:[0,1]
	v_pk_fma_f32 v[38:39], v[84:85], v[38:39], v[42:43] op_sel_hi:[0,1,1]
	s_waitcnt lgkmcnt(7)
	v_pk_add_f32 v[38:39], v[142:143], v[38:39]
	ds_write2st64_b32 v101, v38, v39 offset0:18 offset1:19
	v_xor_b32_e32 v42, 0x80000000, v39
	v_mov_b32_e32 v43, v38
	v_pk_mul_f32 v[42:43], v[0:1], v[42:43] op_sel_hi:[0,1]
	v_pk_fma_f32 v[38:39], v[84:85], v[38:39], v[42:43] op_sel_hi:[0,1,1]
	s_waitcnt lgkmcnt(7)
	v_pk_add_f32 v[38:39], v[144:145], v[38:39]
	ds_write2st64_b32 v102, v38, v39 offset0:20 offset1:21
	v_xor_b32_e32 v42, 0x80000000, v39
	v_mov_b32_e32 v43, v38
	v_pk_mul_f32 v[42:43], v[0:1], v[42:43] op_sel_hi:[0,1]
	v_pk_fma_f32 v[38:39], v[84:85], v[38:39], v[42:43] op_sel_hi:[0,1,1]
	s_waitcnt lgkmcnt(7)
	v_pk_add_f32 v[38:39], v[146:147], v[38:39]
	ds_write2st64_b32 v103, v38, v39 offset0:22 offset1:23
	v_xor_b32_e32 v42, 0x80000000, v39
	v_mov_b32_e32 v43, v38
	v_pk_mul_f32 v[42:43], v[0:1], v[42:43] op_sel_hi:[0,1]
	v_pk_fma_f32 v[38:39], v[84:85], v[38:39], v[42:43] op_sel_hi:[0,1,1]
	s_waitcnt lgkmcnt(7)
	v_pk_add_f32 v[38:39], v[148:149], v[38:39]
	ds_write2st64_b32 v104, v38, v39 offset0:24 offset1:25
	v_xor_b32_e32 v42, 0x80000000, v39
	v_mov_b32_e32 v43, v38
	v_pk_mul_f32 v[42:43], v[0:1], v[42:43] op_sel_hi:[0,1]
	v_pk_fma_f32 v[38:39], v[84:85], v[38:39], v[42:43] op_sel_hi:[0,1,1]
	s_waitcnt lgkmcnt(7)
	v_pk_add_f32 v[38:39], v[150:151], v[38:39]
	ds_write2st64_b32 v105, v38, v39 offset0:26 offset1:27
	v_xor_b32_e32 v42, 0x80000000, v39
	v_mov_b32_e32 v43, v38
	v_pk_mul_f32 v[42:43], v[0:1], v[42:43] op_sel_hi:[0,1]
	v_pk_fma_f32 v[38:39], v[84:85], v[38:39], v[42:43] op_sel_hi:[0,1,1]
	s_waitcnt lgkmcnt(7)
	v_pk_add_f32 v[38:39], v[152:153], v[38:39]
	ds_write2st64_b32 v106, v38, v39 offset0:28 offset1:29
	v_xor_b32_e32 v42, 0x80000000, v39
	v_mov_b32_e32 v43, v38
	v_pk_mul_f32 v[42:43], v[0:1], v[42:43] op_sel_hi:[0,1]
	v_pk_fma_f32 v[38:39], v[84:85], v[38:39], v[42:43] op_sel_hi:[0,1,1]
	s_waitcnt lgkmcnt(7)
	v_pk_add_f32 v[38:39], v[154:155], v[38:39]
	ds_write2st64_b32 v107, v38, v39 offset0:30 offset1:31
	s_waitcnt lgkmcnt(0)
	s_barrier
; __device__ __forceinline__ float bf2f(bf16_t v) { return __uint_as_float(((unsigned)v) << 16); }
; __device__ __forceinline__ bf16_t f2bf(float f) { unsigned u = __float_as_uint(f); u += 0x7FFFu + ((u >> 16) & 1u); return (bf16_t)(u >> 16); }
; __device__ __forceinline__ void s5_pass2_item(PP p, unsigned char* shm, int item, int l) {
;     ...
;         f32x4 y0 = (f32x4){0.f, 0.f, 0.f, 0.f}, y1 = y0;
;         const f32x4* xrow = (const f32x4*)(xs + cc * 132 + quad * 32);
; #pragma unroll
;         for (int i = 0; i < 8; ++i) { const f32x4 xv = xrow[i];
;             y0 = __builtin_amdgcn_mfma_f32_16x16x4f32(xv[0], cmr[4 * i + 0], y0, 0, 0, 0);
;             y1 = __builtin_amdgcn_mfma_f32_16x16x4f32(xv[1], cmr[4 * i + 1], y1, 0, 0, 0);
;             y0 = __builtin_amdgcn_mfma_f32_16x16x4f32(xv[2], cmr[4 * i + 2], y0, 0, 0, 0);
;             y1 = __builtin_amdgcn_mfma_f32_16x16x4f32(xv[3], cmr[4 * i + 3], y1, 0, 0, 0); }
;         const f32x4 y = y0 + y1;
; #pragma unroll
;         for (int r = 0; r < 4; ++r) { const int tl = sc * 16 + quad * 4 + r;
;             const float v = y[r] + dsk * bf2f(proj[PJ_UA + (row0 + tl) * 512 + g * 16 + cc]);
;             const float z = 0.7978845608028654f * (v + 0.044715f * v * v * v);
;             const float th = 1.0f - 2.0f / (__expf(2.0f * z) + 1.0f);
;             Gout[(row0 + tl) * 512 + g * 16 + cc] = f2bf(0.5f * v * (1.0f + th)); }
	v_or_b32_e32 v216, 32, v82
	v_mov_b32_e32 v217, v83
	v_lshlrev_b64 v[216:217], 9, v[216:217]
	v_lshl_add_u64 v[216:217], v[216:217], 0, v[50:51]
	v_lshlrev_b64 v[216:217], 1, v[216:217]
	v_lshl_add_u64 v[216:217], s[8:9], 0, v[216:217]
	global_load_ushort v208, v[216:217], off
	global_load_ushort v209, v[216:217], off offset:1024
	global_load_ushort v210, v[216:217], off offset:2048
	global_load_ushort v211, v[216:217], off offset:3072
	ds_read_b128 v[40:43], v89
	ds_read_b128 v[44:47], v89 offset:16
	ds_read_b128 v[110:113], v89 offset:32
	ds_read_b128 v[114:117], v89 offset:48
	s_waitcnt lgkmcnt(3)
	v_mfma_f32_16x16x4_f32 v[118:121], v40, v97, 0
	v_mfma_f32_16x16x4_f32 v[122:125], v41, v96, 0
	v_mfma_f32_16x16x4_f32 v[118:121], v42, v95, v[118:121]
	v_mfma_f32_16x16x4_f32 v[40:43], v43, v94, v[122:125]
	s_waitcnt lgkmcnt(2)
	v_mfma_f32_16x16x4_f32 v[118:121], v44, v93, v[118:121]
	v_mfma_f32_16x16x4_f32 v[40:43], v45, v92, v[40:43]
	v_mfma_f32_16x16x4_f32 v[118:121], v46, v91, v[118:121]
	v_mfma_f32_16x16x4_f32 v[40:43], v47, v88, v[40:43]
	s_waitcnt lgkmcnt(1)
	v_mfma_f32_16x16x4_f32 v[44:47], v110, v85, v[118:121]
	v_mfma_f32_16x16x4_f32 v[40:43], v111, v55, v[40:43]
	v_mfma_f32_16x16x4_f32 v[44:47], v112, v56, v[44:47]
	v_mfma_f32_16x16x4_f32 v[40:43], v113, v57, v[40:43]
	ds_read_b128 v[110:113], v89 offset:64
	s_waitcnt lgkmcnt(1)
	v_mfma_f32_16x16x4_f32 v[44:47], v114, v58, v[44:47]
	v_mfma_f32_16x16x4_f32 v[40:43], v115, v59, v[40:43]
	v_mfma_f32_16x16x4_f32 v[44:47], v116, v60, v[44:47]
	v_mfma_f32_16x16x4_f32 v[40:43], v117, v61, v[40:43]
	s_waitcnt lgkmcnt(0)
	v_mfma_f32_16x16x4_f32 v[44:47], v110, v62, v[44:47]
	v_mfma_f32_16x16x4_f32 v[40:43], v111, v63, v[40:43]
	v_mfma_f32_16x16x4_f32 v[44:47], v112, v64, v[44:47]
	v_mfma_f32_16x16x4_f32 v[40:43], v113, v65, v[40:43]
	ds_read_b128 v[110:113], v89 offset:80
	s_waitcnt lgkmcnt(0)
	v_mfma_f32_16x16x4_f32 v[44:47], v110, v66, v[44:47]
	v_mfma_f32_16x16x4_f32 v[40:43], v111, v67, v[40:43]
	v_mfma_f32_16x16x4_f32 v[44:47], v112, v68, v[44:47]
	v_mfma_f32_16x16x4_f32 v[40:43], v113, v69, v[40:43]
	ds_read_b128 v[110:113], v89 offset:96
	s_waitcnt lgkmcnt(0)
	v_mfma_f32_16x16x4_f32 v[44:47], v110, v70, v[44:47]
	v_mfma_f32_16x16x4_f32 v[40:43], v111, v71, v[40:43]
	v_mfma_f32_16x16x4_f32 v[44:47], v112, v72, v[44:47]
	v_mfma_f32_16x16x4_f32 v[40:43], v113, v73, v[40:43]
	ds_read_b128 v[110:113], v89 offset:112
	s_waitcnt lgkmcnt(0)
	v_mfma_f32_16x16x4_f32 v[44:47], v110, v74, v[44:47]
	v_mfma_f32_16x16x4_f32 v[40:43], v111, v75, v[40:43]
	v_mfma_f32_16x16x4_f32 v[44:47], v112, v76, v[44:47]
	v_mfma_f32_16x16x4_f32 v[40:43], v113, v77, v[40:43]
	s_nop 9
	v_pk_add_f32 v[40:41], v[44:45], v[40:41]
	v_or_b32_e32 v44, 32, v82
	v_mov_b32_e32 v45, v83
	v_lshlrev_b64 v[44:45], 9, v[44:45]
	v_lshl_add_u64 v[44:45], v[44:45], 0, v[50:51]
	v_lshlrev_b64 v[44:45], 1, v[44:45]
	v_pk_add_f32 v[42:43], v[46:47], v[42:43]
	v_lshl_add_u64 v[46:47], s[8:9], 0, v[44:45]
	v_lshl_add_u64 v[44:45], s[28:29], 0, v[44:45]
	s_waitcnt vmcnt(3)
	v_lshlrev_b32_e32 v46, 16, v208
	v_fma_f32 v40, v54, v46, v40
	v_mul_f32_e32 v46, 0x3d372713, v40
	v_mul_f32_e32 v46, v40, v46
	v_fma_f32 v46, v40, v46, v40
	v_mul_f32_e32 v46, 0x3f4c422a, v46
	v_add_f32_e32 v46, v46, v46
	v_mul_f32_e32 v46, 0x3fb8aa3b, v46
	v_exp_f32_e32 v46, v46
	v_mul_f32_e32 v40, 0.5, v40
	v_add_f32_e32 v46, 1.0, v46
	v_div_scale_f32 v47, s[2:3], v46, v46, 2.0
	v_rcp_f32_e32 v48, v47
	s_nop 0
	v_fma_f32 v49, -v47, v48, 1.0
	v_fmac_f32_e32 v48, v49, v48
	v_div_scale_f32 v49, vcc, 2.0, v46, 2.0
	v_mul_f32_e32 v52, v49, v48
	v_fma_f32 v53, -v47, v52, v49
	v_fmac_f32_e32 v52, v53, v48
	v_fma_f32 v47, -v47, v52, v49
	v_div_fmas_f32 v47, v47, v48, v52
	v_div_fixup_f32 v46, v47, v46, 2.0
	v_sub_f32_e32 v46, 1.0, v46
	v_add_f32_e32 v46, 1.0, v46
	v_mul_f32_e32 v40, v40, v46
	v_bfe_u32 v46, v40, 16, 1
	v_add3_u32 v40, v40, v46, s31
	global_store_short_d16_hi v[44:45], v40, off
	v_or_b32_e32 v44, 33, v82
	v_mov_b32_e32 v45, v83
	v_lshlrev_b64 v[44:45], 9, v[44:45]
	v_lshl_add_u64 v[44:45], v[44:45], 0, v[50:51]
	v_lshlrev_b64 v[44:45], 1, v[44:45]
	v_lshl_add_u64 v[46:47], s[8:9], 0, v[44:45]
	s_waitcnt vmcnt(3)
	v_lshlrev_b32_e32 v40, 16, v209
	v_fmac_f32_e32 v41, v54, v40
	v_mul_f32_e32 v40, 0x3d372713, v41
	v_mul_f32_e32 v40, v41, v40
	v_fma_f32 v40, v41, v40, v41
	v_mul_f32_e32 v40, 0x3f4c422a, v40
	v_add_f32_e32 v40, v40, v40
	v_mul_f32_e32 v40, 0x3fb8aa3b, v40
	v_exp_f32_e32 v40, v40
	v_mul_f32_e32 v41, 0.5, v41
	v_add_f32_e32 v40, 1.0, v40
	v_div_scale_f32 v46, s[2:3], v40, v40, 2.0
	v_rcp_f32_e32 v47, v46
	s_nop 0
	v_fma_f32 v48, -v46, v47, 1.0
	v_fmac_f32_e32 v47, v48, v47
	v_div_scale_f32 v48, vcc, 2.0, v40, 2.0
	v_mul_f32_e32 v49, v48, v47
	v_fma_f32 v52, -v46, v49, v48
	v_fmac_f32_e32 v49, v52, v47
	v_fma_f32 v46, -v46, v49, v48
	v_div_fmas_f32 v46, v46, v47, v49
	v_div_fixup_f32 v40, v46, v40, 2.0
	v_sub_f32_e32 v40, 1.0, v40
	v_add_f32_e32 v40, 1.0, v40
	v_mul_f32_e32 v40, v41, v40
	v_bfe_u32 v41, v40, 16, 1
	v_add3_u32 v46, v40, v41, s31
	v_lshl_add_u64 v[40:41], s[28:29], 0, v[44:45]
	global_store_short_d16_hi v[40:41], v46, off
	v_or_b32_e32 v40, 34, v82
	v_mov_b32_e32 v41, v83
	v_lshlrev_b64 v[40:41], 9, v[40:41]
	v_lshl_add_u64 v[40:41], v[40:41], 0, v[50:51]
	v_lshlrev_b64 v[40:41], 1, v[40:41]
	v_lshl_add_u64 v[44:45], s[8:9], 0, v[40:41]
	v_lshl_add_u64 v[40:41], s[28:29], 0, v[40:41]
	s_waitcnt vmcnt(3)
; __device__ __forceinline__ float bf2f(bf16_t v) { return __uint_as_float(((unsigned)v) << 16); }
; __device__ __forceinline__ bf16_t f2bf(float f) { unsigned u = __float_as_uint(f); u += 0x7FFFu + ((u >> 16) & 1u); return (bf16_t)(u >> 16); }
; __device__ __forceinline__ void s5_pass2_item(PP p, unsigned char* shm, int item, int l) {
;     ...
;     for (int sc = 0; sc < 4; ++sc) {
;         s5_bu16(f, uf[sc], buL, lane);
;         __syncthreads();
; #pragma unroll
;         for (int t = 0; t < 16; ++t) { s5_rec(q, *(const f32x2*)(buL + (t * 64 + lane) * 2), x); xs[t * 132 + lane] = x.x; xs[t * 132 + 64 + lane] = x.y; }
;     ...
;         const f32x4 y = y0 + y1;
; #pragma unroll
;         for (int r = 0; r < 4; ++r) { const int tl = sc * 16 + quad * 4 + r;
;             const float v = y[r] + dsk * bf2f(proj[PJ_UA + (row0 + tl) * 512 + g * 16 + cc]);
;             const float z = 0.7978845608028654f * (v + 0.044715f * v * v * v);
;             const float th = 1.0f - 2.0f / (__expf(2.0f * z) + 1.0f);
;             Gout[(row0 + tl) * 512 + g * 16 + cc] = f2bf(0.5f * v * (1.0f + th)); }
	v_lshlrev_b32_e32 v44, 16, v210
	v_fma_f32 v42, v54, v44, v42
	v_mul_f32_e32 v44, 0x3d372713, v42
	v_mul_f32_e32 v44, v42, v44
	v_fma_f32 v44, v42, v44, v42
	v_mul_f32_e32 v44, 0x3f4c422a, v44
	v_add_f32_e32 v44, v44, v44
	v_mul_f32_e32 v44, 0x3fb8aa3b, v44
	v_exp_f32_e32 v44, v44
	v_mul_f32_e32 v42, 0.5, v42
	v_add_f32_e32 v44, 1.0, v44
	v_div_scale_f32 v45, s[2:3], v44, v44, 2.0
	v_rcp_f32_e32 v46, v45
	s_nop 0
	v_fma_f32 v47, -v45, v46, 1.0
	v_fmac_f32_e32 v46, v47, v46
	v_div_scale_f32 v47, vcc, 2.0, v44, 2.0
	v_mul_f32_e32 v48, v47, v46
	v_fma_f32 v49, -v45, v48, v47
	v_fmac_f32_e32 v48, v49, v46
	v_fma_f32 v45, -v45, v48, v47
	v_div_fmas_f32 v45, v45, v46, v48
	v_div_fixup_f32 v44, v45, v44, 2.0
	v_sub_f32_e32 v44, 1.0, v44
	v_add_f32_e32 v44, 1.0, v44
	v_mul_f32_e32 v42, v42, v44
	v_bfe_u32 v44, v42, 16, 1
	v_add3_u32 v42, v42, v44, s31
	global_store_short_d16_hi v[40:41], v42, off
	v_or_b32_e32 v40, 35, v82
	v_mov_b32_e32 v41, v83
	v_lshlrev_b64 v[40:41], 9, v[40:41]
	v_lshl_add_u64 v[40:41], v[40:41], 0, v[50:51]
	v_lshlrev_b64 v[40:41], 1, v[40:41]
	v_lshl_add_u64 v[44:45], s[8:9], 0, v[40:41]
	v_lshl_add_u64 v[40:41], s[28:29], 0, v[40:41]
	s_waitcnt vmcnt(3)
	v_lshlrev_b32_e32 v42, 16, v211
	v_fmac_f32_e32 v43, v54, v42
	v_mul_f32_e32 v42, 0x3d372713, v43
	v_mul_f32_e32 v42, v43, v42
	v_fma_f32 v42, v43, v42, v43
	v_mul_f32_e32 v42, 0x3f4c422a, v42
	v_add_f32_e32 v42, v42, v42
	v_mul_f32_e32 v42, 0x3fb8aa3b, v42
	v_exp_f32_e32 v42, v42
	v_mul_f32_e32 v43, 0.5, v43
	v_add_f32_e32 v42, 1.0, v42
	v_div_scale_f32 v44, s[2:3], v42, v42, 2.0
	v_rcp_f32_e32 v45, v44
	s_nop 0
	v_fma_f32 v46, -v44, v45, 1.0
	v_fmac_f32_e32 v45, v46, v45
	v_div_scale_f32 v46, vcc, 2.0, v42, 2.0
	v_mul_f32_e32 v47, v46, v45
	v_fma_f32 v48, -v44, v47, v46
	v_fmac_f32_e32 v47, v48, v45
	v_fma_f32 v44, -v44, v47, v46
	v_div_fmas_f32 v44, v44, v45, v47
	v_div_fixup_f32 v42, v44, v42, 2.0
	v_sub_f32_e32 v42, 1.0, v42
	v_add_f32_e32 v42, 1.0, v42
	v_mul_f32_e32 v42, v43, v42
	v_bfe_u32 v43, v42, 16, 1
	v_add3_u32 v42, v42, v43, s31
	global_store_short_d16_hi v[40:41], v42, off
	v_mfma_f32_16x16x32_bf16 v[40:43], v[2:5], v[26:29], 0
	s_barrier
	v_mfma_f32_16x16x32_bf16 v[26:29], v[2:5], v[34:37], 0
	v_mfma_f32_16x16x32_bf16 v[2:5], v[2:5], v[6:9], 0
	s_nop 4
	v_mov_b32_e32 v34, v40
	s_nop 0
	v_mov_b32_e32 v35, v26
	v_mov_b32_e32 v26, v41
	v_mov_b32_e32 v36, v42
	v_mov_b32_e32 v37, v28
	v_mov_b32_e32 v40, v22
	v_mov_b32_e32 v41, v30
	v_mov_b32_e32 v30, v23
	v_mov_b32_e32 v22, v24
	v_mov_b32_e32 v23, v32
	ds_write2_b64 v108, v[36:37], v[22:23] offset0:128 offset1:144
	v_mov_b32_e32 v23, v14
	v_mov_b32_e32 v14, v19
	v_mov_b32_e32 v6, v10
	v_mov_b32_e32 v7, v2
	v_mov_b32_e32 v2, v11
	v_mov_b32_e32 v28, v43
	v_mov_b32_e32 v32, v25
	v_mov_b32_e32 v22, v18
	ds_write2_b64 v108, v[30:31], v[14:15] offset0:80 offset1:96
	v_mov_b32_e32 v14, v20
	v_mov_b32_e32 v15, v16
	v_mov_b32_e32 v16, v21
	ds_write2st64_b64 v99, v[6:7], v[2:3] offset0:8 offset1:9
	v_mov_b32_e32 v2, v12
	v_mov_b32_e32 v3, v4
	v_mov_b32_e32 v4, v13
	ds_write2_b64 v108, v[34:35], v[40:41] offset1:16
	ds_write2_b64 v108, v[22:23], v[26:27] offset0:32 offset1:64
	ds_write2_b64 v108, v[14:15], v[28:29] offset0:160 offset1:192
	ds_write2_b64 v108, v[32:33], v[16:17] offset0:208 offset1:224
	ds_write2st64_b64 v99, v[2:3], v[4:5] offset0:10 offset1:11
	s_waitcnt lgkmcnt(0)
	s_barrier
	ds_read_b64 v[140:141], v90 offset:4096
	ds_read_b64 v[142:143], v90 offset:4608
	ds_read_b64 v[144:145], v90 offset:5120
	ds_read_b64 v[146:147], v90 offset:5632
	ds_read_b64 v[148:149], v90 offset:6144
	ds_read_b64 v[150:151], v90 offset:6656
	ds_read_b64 v[152:153], v90 offset:7168
	ds_read_b64 v[154:155], v90 offset:7680
	v_xor_b32_e32 v4, 0x80000000, v39
	v_mov_b32_e32 v5, v38
	v_pk_mul_f32 v[4:5], v[0:1], v[4:5] op_sel_hi:[0,1]
	v_pk_fma_f32 v[4:5], v[84:85], v[38:39], v[4:5] op_sel_hi:[0,1,1]
	s_waitcnt lgkmcnt(7)
	v_pk_add_f32 v[2:3], v[4:5], v[140:141]
	ds_write2st64_b32 v98, v2, v3 offset1:1
	v_xor_b32_e32 v6, 0x80000000, v3
	v_mov_b32_e32 v7, v2
	v_pk_mul_f32 v[6:7], v[0:1], v[6:7] op_sel_hi:[0,1]
	v_pk_fma_f32 v[2:3], v[84:85], v[2:3], v[6:7] op_sel_hi:[0,1,1]
	s_waitcnt lgkmcnt(7)
	v_pk_add_f32 v[2:3], v[142:143], v[2:3]
	ds_write2_b32 v98, v2, v3 offset0:132 offset1:196
	v_xor_b32_e32 v6, 0x80000000, v3
	v_mov_b32_e32 v7, v2
	v_pk_mul_f32 v[6:7], v[0:1], v[6:7] op_sel_hi:[0,1]
	v_pk_fma_f32 v[2:3], v[84:85], v[2:3], v[6:7] op_sel_hi:[0,1,1]
	s_waitcnt lgkmcnt(7)
	v_pk_add_f32 v[2:3], v[144:145], v[2:3]
	ds_write2st64_b32 v78, v2, v3 offset0:4 offset1:5
	v_xor_b32_e32 v6, 0x80000000, v3
	v_mov_b32_e32 v7, v2
	v_pk_mul_f32 v[6:7], v[0:1], v[6:7] op_sel_hi:[0,1]
	v_pk_fma_f32 v[2:3], v[84:85], v[2:3], v[6:7] op_sel_hi:[0,1,1]
	s_waitcnt lgkmcnt(7)
	v_pk_add_f32 v[2:3], v[146:147], v[2:3]
	ds_write2st64_b32 v79, v2, v3 offset0:6 offset1:7
	v_xor_b32_e32 v6, 0x80000000, v3
	v_mov_b32_e32 v7, v2
	v_pk_mul_f32 v[6:7], v[0:1], v[6:7] op_sel_hi:[0,1]
	v_pk_fma_f32 v[2:3], v[84:85], v[2:3], v[6:7] op_sel_hi:[0,1,1]
	s_waitcnt lgkmcnt(7)
	v_pk_add_f32 v[2:3], v[148:149], v[2:3]
	ds_write2st64_b32 v80, v2, v3 offset0:8 offset1:9
	v_xor_b32_e32 v6, 0x80000000, v3
	v_mov_b32_e32 v7, v2
	v_pk_mul_f32 v[6:7], v[0:1], v[6:7] op_sel_hi:[0,1]
	v_pk_fma_f32 v[2:3], v[84:85], v[2:3], v[6:7] op_sel_hi:[0,1,1]
	s_waitcnt lgkmcnt(7)
	v_pk_add_f32 v[2:3], v[150:151], v[2:3]
	ds_write2st64_b32 v81, v2, v3 offset0:10 offset1:11
	v_xor_b32_e32 v6, 0x80000000, v3
	v_mov_b32_e32 v7, v2
	v_pk_mul_f32 v[6:7], v[0:1], v[6:7] op_sel_hi:[0,1]
	v_pk_fma_f32 v[2:3], v[84:85], v[2:3], v[6:7] op_sel_hi:[0,1,1]
	s_waitcnt lgkmcnt(7)
; __device__ __forceinline__ void s5_pass2_item(PP p, unsigned char* shm, int item, int l) {
;     ...
;     for (int sc = 0; sc < 4; ++sc) {
;         s5_bu16(f, uf[sc], buL, lane);
;         __syncthreads();
; #pragma unroll
;         for (int t = 0; t < 16; ++t) { s5_rec(q, *(const f32x2*)(buL + (t * 64 + lane) * 2), x); xs[t * 132 + lane] = x.x; xs[t * 132 + 64 + lane] = x.y; }
	v_pk_add_f32 v[2:3], v[152:153], v[2:3]
	ds_write2st64_b32 v86, v2, v3 offset0:12 offset1:13
	v_xor_b32_e32 v6, 0x80000000, v3
	v_mov_b32_e32 v7, v2
	v_pk_mul_f32 v[6:7], v[0:1], v[6:7] op_sel_hi:[0,1]
	v_pk_fma_f32 v[2:3], v[84:85], v[2:3], v[6:7] op_sel_hi:[0,1,1]
	s_waitcnt lgkmcnt(7)
	v_pk_add_f32 v[2:3], v[154:155], v[2:3]
	ds_write2st64_b32 v87, v2, v3 offset0:14 offset1:15
	ds_read_b64 v[140:141], v90 offset:8192
	ds_read_b64 v[142:143], v90 offset:8704
	ds_read_b64 v[144:145], v90 offset:9216
	ds_read_b64 v[146:147], v90 offset:9728
	ds_read_b64 v[148:149], v90 offset:10240
	ds_read_b64 v[150:151], v90 offset:10752
	ds_read_b64 v[152:153], v90 offset:11264
	ds_read_b64 v[154:155], v90 offset:11776
	v_xor_b32_e32 v6, 0x80000000, v3
	v_mov_b32_e32 v7, v2
	v_pk_mul_f32 v[6:7], v[0:1], v[6:7] op_sel_hi:[0,1]
	v_pk_fma_f32 v[2:3], v[84:85], v[2:3], v[6:7] op_sel_hi:[0,1,1]
	s_waitcnt lgkmcnt(7)
	v_pk_add_f32 v[2:3], v[140:141], v[2:3]
	ds_write2st64_b32 v100, v2, v3 offset0:16 offset1:17
	v_xor_b32_e32 v6, 0x80000000, v3
	v_mov_b32_e32 v7, v2
	v_pk_mul_f32 v[6:7], v[0:1], v[6:7] op_sel_hi:[0,1]
	v_pk_fma_f32 v[2:3], v[84:85], v[2:3], v[6:7] op_sel_hi:[0,1,1]
	s_waitcnt lgkmcnt(7)
	v_pk_add_f32 v[2:3], v[142:143], v[2:3]
	ds_write2st64_b32 v101, v2, v3 offset0:18 offset1:19
	v_xor_b32_e32 v6, 0x80000000, v3
	v_mov_b32_e32 v7, v2
	v_pk_mul_f32 v[6:7], v[0:1], v[6:7] op_sel_hi:[0,1]
	v_pk_fma_f32 v[2:3], v[84:85], v[2:3], v[6:7] op_sel_hi:[0,1,1]
	s_waitcnt lgkmcnt(7)
	v_pk_add_f32 v[2:3], v[144:145], v[2:3]
	ds_write2st64_b32 v102, v2, v3 offset0:20 offset1:21
	v_xor_b32_e32 v6, 0x80000000, v3
	v_mov_b32_e32 v7, v2
	v_pk_mul_f32 v[6:7], v[0:1], v[6:7] op_sel_hi:[0,1]
	v_pk_fma_f32 v[2:3], v[84:85], v[2:3], v[6:7] op_sel_hi:[0,1,1]
	s_waitcnt lgkmcnt(7)
	v_pk_add_f32 v[2:3], v[146:147], v[2:3]
	ds_write2st64_b32 v103, v2, v3 offset0:22 offset1:23
	v_xor_b32_e32 v6, 0x80000000, v3
	v_mov_b32_e32 v7, v2
	v_pk_mul_f32 v[6:7], v[0:1], v[6:7] op_sel_hi:[0,1]
	v_pk_fma_f32 v[2:3], v[84:85], v[2:3], v[6:7] op_sel_hi:[0,1,1]
	s_waitcnt lgkmcnt(7)
	v_pk_add_f32 v[2:3], v[148:149], v[2:3]
	ds_write2st64_b32 v104, v2, v3 offset0:24 offset1:25
	v_xor_b32_e32 v6, 0x80000000, v3
	v_mov_b32_e32 v7, v2
	v_pk_mul_f32 v[6:7], v[0:1], v[6:7] op_sel_hi:[0,1]
	v_pk_fma_f32 v[2:3], v[84:85], v[2:3], v[6:7] op_sel_hi:[0,1,1]
	s_waitcnt lgkmcnt(7)
	v_pk_add_f32 v[2:3], v[150:151], v[2:3]
	ds_write2st64_b32 v105, v2, v3 offset0:26 offset1:27
	v_xor_b32_e32 v6, 0x80000000, v3
	v_mov_b32_e32 v7, v2
	v_pk_mul_f32 v[6:7], v[0:1], v[6:7] op_sel_hi:[0,1]
	v_pk_fma_f32 v[2:3], v[84:85], v[2:3], v[6:7] op_sel_hi:[0,1,1]
	s_waitcnt lgkmcnt(7)
	v_pk_add_f32 v[2:3], v[152:153], v[2:3]
	ds_write2st64_b32 v106, v2, v3 offset0:28 offset1:29
	v_xor_b32_e32 v6, 0x80000000, v3
	v_mov_b32_e32 v7, v2
	v_pk_mul_f32 v[6:7], v[0:1], v[6:7] op_sel_hi:[0,1]
	v_pk_fma_f32 v[2:3], v[84:85], v[2:3], v[6:7] op_sel_hi:[0,1,1]
	s_waitcnt lgkmcnt(7)
	v_pk_add_f32 v[2:3], v[154:155], v[2:3]
	ds_write2st64_b32 v107, v2, v3 offset0:30 offset1:31
	s_waitcnt lgkmcnt(0)
	s_barrier
; __device__ __forceinline__ float bf2f(bf16_t v) { return __uint_as_float(((unsigned)v) << 16); }
; __device__ __forceinline__ bf16_t f2bf(float f) { unsigned u = __float_as_uint(f); u += 0x7FFFu + ((u >> 16) & 1u); return (bf16_t)(u >> 16); }
; __device__ __forceinline__ void s5_pass2_item(PP p, unsigned char* shm, int item, int l) {
;     ...
;         f32x4 y0 = (f32x4){0.f, 0.f, 0.f, 0.f}, y1 = y0;
;         const f32x4* xrow = (const f32x4*)(xs + cc * 132 + quad * 32);
; #pragma unroll
;         for (int i = 0; i < 8; ++i) { const f32x4 xv = xrow[i];
;             y0 = __builtin_amdgcn_mfma_f32_16x16x4f32(xv[0], cmr[4 * i + 0], y0, 0, 0, 0);
;             y1 = __builtin_amdgcn_mfma_f32_16x16x4f32(xv[1], cmr[4 * i + 1], y1, 0, 0, 0);
;             y0 = __builtin_amdgcn_mfma_f32_16x16x4f32(xv[2], cmr[4 * i + 2], y0, 0, 0, 0);
;             y1 = __builtin_amdgcn_mfma_f32_16x16x4f32(xv[3], cmr[4 * i + 3], y1, 0, 0, 0); }
;         const f32x4 y = y0 + y1;
; #pragma unroll
;         for (int r = 0; r < 4; ++r) { const int tl = sc * 16 + quad * 4 + r;
;             const float v = y[r] + dsk * bf2f(proj[PJ_UA + (row0 + tl) * 512 + g * 16 + cc]);
;             const float z = 0.7978845608028654f * (v + 0.044715f * v * v * v);
;             const float th = 1.0f - 2.0f / (__expf(2.0f * z) + 1.0f);
;             Gout[(row0 + tl) * 512 + g * 16 + cc] = f2bf(0.5f * v * (1.0f + th)); }
;         __syncthreads();
	v_or_b32_e32 v216, 48, v82
	v_mov_b32_e32 v217, v83
	v_lshlrev_b64 v[216:217], 9, v[216:217]
	v_lshl_add_u64 v[216:217], v[216:217], 0, v[50:51]
	v_lshlrev_b64 v[216:217], 1, v[216:217]
	v_lshl_add_u64 v[216:217], s[8:9], 0, v[216:217]
	global_load_ushort v212, v[216:217], off
	global_load_ushort v213, v[216:217], off offset:1024
	global_load_ushort v214, v[216:217], off offset:2048
	global_load_ushort v215, v[216:217], off offset:3072
	ds_read_b128 v[2:5], v89
	ds_read_b128 v[6:9], v89 offset:16
	ds_read_b128 v[10:13], v89 offset:32
	ds_read_b128 v[14:17], v89 offset:48
	s_waitcnt lgkmcnt(3)
	v_mfma_f32_16x16x4_f32 v[18:21], v2, v97, 0
	v_mfma_f32_16x16x4_f32 v[22:25], v3, v96, 0
	v_mfma_f32_16x16x4_f32 v[18:21], v4, v95, v[18:21]
	v_mfma_f32_16x16x4_f32 v[2:5], v5, v94, v[22:25]
	s_waitcnt lgkmcnt(2)
	v_mfma_f32_16x16x4_f32 v[18:21], v6, v93, v[18:21]
	v_mfma_f32_16x16x4_f32 v[2:5], v7, v92, v[2:5]
	v_mfma_f32_16x16x4_f32 v[18:21], v8, v91, v[18:21]
	v_mfma_f32_16x16x4_f32 v[2:5], v9, v88, v[2:5]
	s_waitcnt lgkmcnt(1)
	v_mfma_f32_16x16x4_f32 v[6:9], v10, v85, v[18:21]
	v_mfma_f32_16x16x4_f32 v[2:5], v11, v55, v[2:5]
	v_mfma_f32_16x16x4_f32 v[6:9], v12, v56, v[6:9]
	v_mfma_f32_16x16x4_f32 v[2:5], v13, v57, v[2:5]
	ds_read_b128 v[10:13], v89 offset:64
	s_waitcnt lgkmcnt(1)
	v_mfma_f32_16x16x4_f32 v[6:9], v14, v58, v[6:9]
	v_mfma_f32_16x16x4_f32 v[2:5], v15, v59, v[2:5]
	v_mfma_f32_16x16x4_f32 v[6:9], v16, v60, v[6:9]
	v_mfma_f32_16x16x4_f32 v[2:5], v17, v61, v[2:5]
	s_waitcnt lgkmcnt(0)
	v_mfma_f32_16x16x4_f32 v[6:9], v10, v62, v[6:9]
	v_mfma_f32_16x16x4_f32 v[2:5], v11, v63, v[2:5]
	v_mfma_f32_16x16x4_f32 v[6:9], v12, v64, v[6:9]
	v_mfma_f32_16x16x4_f32 v[2:5], v13, v65, v[2:5]
	ds_read_b128 v[10:13], v89 offset:80
	s_waitcnt lgkmcnt(0)
	v_mfma_f32_16x16x4_f32 v[6:9], v10, v66, v[6:9]
	v_mfma_f32_16x16x4_f32 v[2:5], v11, v67, v[2:5]
	v_mfma_f32_16x16x4_f32 v[6:9], v12, v68, v[6:9]
	v_mfma_f32_16x16x4_f32 v[2:5], v13, v69, v[2:5]
	ds_read_b128 v[10:13], v89 offset:96
	s_waitcnt lgkmcnt(0)
	v_mfma_f32_16x16x4_f32 v[6:9], v10, v70, v[6:9]
	v_mfma_f32_16x16x4_f32 v[2:5], v11, v71, v[2:5]
	v_mfma_f32_16x16x4_f32 v[6:9], v12, v72, v[6:9]
	v_mfma_f32_16x16x4_f32 v[2:5], v13, v73, v[2:5]
	ds_read_b128 v[10:13], v89 offset:112
	s_waitcnt lgkmcnt(0)
	v_mfma_f32_16x16x4_f32 v[6:9], v10, v74, v[6:9]
	v_mfma_f32_16x16x4_f32 v[2:5], v11, v75, v[2:5]
	v_mfma_f32_16x16x4_f32 v[6:9], v12, v76, v[6:9]
	v_mfma_f32_16x16x4_f32 v[10:13], v13, v77, v[2:5]
	s_nop 9
	v_pk_add_f32 v[4:5], v[6:7], v[10:11]
	v_or_b32_e32 v6, 48, v82
	v_mov_b32_e32 v7, v83
	v_lshlrev_b64 v[6:7], 9, v[6:7]
	v_lshl_add_u64 v[6:7], v[6:7], 0, v[50:51]
	v_lshlrev_b64 v[6:7], 1, v[6:7]
	v_pk_add_f32 v[2:3], v[8:9], v[12:13]
	v_lshl_add_u64 v[8:9], s[8:9], 0, v[6:7]
	v_lshl_add_u64 v[6:7], s[28:29], 0, v[6:7]
	s_waitcnt vmcnt(3)
	v_lshlrev_b32_e32 v0, 16, v212
	v_fma_f32 v0, v54, v0, v4
	v_mul_f32_e32 v4, 0x3d372713, v0
	v_mul_f32_e32 v4, v0, v4
	v_fma_f32 v4, v0, v4, v0
	v_mul_f32_e32 v4, 0x3f4c422a, v4
	v_add_f32_e32 v4, v4, v4
	v_mul_f32_e32 v4, 0x3fb8aa3b, v4
	v_exp_f32_e32 v4, v4
	v_mul_f32_e32 v0, 0.5, v0
	v_add_f32_e32 v4, 1.0, v4
	v_div_scale_f32 v8, s[2:3], v4, v4, 2.0
	v_rcp_f32_e32 v9, v8
	s_nop 0
	v_fma_f32 v10, -v8, v9, 1.0
	v_fmac_f32_e32 v9, v10, v9
	v_div_scale_f32 v10, vcc, 2.0, v4, 2.0
	v_mul_f32_e32 v11, v10, v9
	v_fma_f32 v12, -v8, v11, v10
	v_fmac_f32_e32 v11, v12, v9
	v_fma_f32 v8, -v8, v11, v10
	v_div_fmas_f32 v8, v8, v9, v11
	v_div_fixup_f32 v4, v8, v4, 2.0
	v_sub_f32_e32 v4, 1.0, v4
	v_add_f32_e32 v4, 1.0, v4
	v_mul_f32_e32 v0, v0, v4
	v_bfe_u32 v4, v0, 16, 1
	v_add3_u32 v0, v0, v4, s31
	global_store_short_d16_hi v[6:7], v0, off
	v_or_b32_e32 v6, 49, v82
	v_mov_b32_e32 v7, v83
	v_lshlrev_b64 v[6:7], 9, v[6:7]
	v_lshl_add_u64 v[6:7], v[6:7], 0, v[50:51]
	v_lshlrev_b64 v[6:7], 1, v[6:7]
	v_lshl_add_u64 v[8:9], s[8:9], 0, v[6:7]
	s_waitcnt vmcnt(3)
	v_lshlrev_b32_e32 v0, 16, v213
	v_fmac_f32_e32 v5, v54, v0
	v_mul_f32_e32 v0, 0x3d372713, v5
	v_mul_f32_e32 v0, v5, v0
	v_fma_f32 v0, v5, v0, v5
	v_mul_f32_e32 v0, 0x3f4c422a, v0
	v_add_f32_e32 v0, v0, v0
	v_mul_f32_e32 v0, 0x3fb8aa3b, v0
	v_exp_f32_e32 v0, v0
	s_nop 0
	v_add_f32_e32 v0, 1.0, v0
	v_div_scale_f32 v4, s[2:3], v0, v0, 2.0
	v_rcp_f32_e32 v8, v4
	s_nop 0
	v_fma_f32 v9, -v4, v8, 1.0
	v_fmac_f32_e32 v8, v9, v8
	v_div_scale_f32 v9, vcc, 2.0, v0, 2.0
	v_mul_f32_e32 v10, v9, v8
	v_fma_f32 v11, -v4, v10, v9
	v_fmac_f32_e32 v10, v11, v8
	v_fma_f32 v4, -v4, v10, v9
	v_div_fmas_f32 v4, v4, v8, v10
	v_div_fixup_f32 v0, v4, v0, 2.0
	v_sub_f32_e32 v0, 1.0, v0
	v_mul_f32_e32 v4, 0.5, v5
	v_add_f32_e32 v0, 1.0, v0
	v_mul_f32_e32 v0, v4, v0
	v_bfe_u32 v4, v0, 16, 1
	v_add3_u32 v0, v0, v4, s31
	v_lshl_add_u64 v[4:5], s[28:29], 0, v[6:7]
	global_store_short_d16_hi v[4:5], v0, off
	v_or_b32_e32 v4, 50, v82
	v_mov_b32_e32 v5, v83
	v_lshlrev_b64 v[4:5], 9, v[4:5]
	v_lshl_add_u64 v[4:5], v[4:5], 0, v[50:51]
	v_lshlrev_b64 v[4:5], 1, v[4:5]
	v_lshl_add_u64 v[6:7], s[8:9], 0, v[4:5]
	v_lshl_add_u64 v[4:5], s[28:29], 0, v[4:5]
	v_or_b32_e32 v82, 51, v82
	s_waitcnt vmcnt(3)
	v_lshlrev_b32_e32 v0, 16, v214
	v_fma_f32 v0, v54, v0, v2
	v_mul_f32_e32 v2, 0x3d372713, v0
	v_mul_f32_e32 v2, v0, v2
	v_fma_f32 v2, v0, v2, v0
	v_mul_f32_e32 v2, 0x3f4c422a, v2
	v_add_f32_e32 v2, v2, v2
	v_mul_f32_e32 v2, 0x3fb8aa3b, v2
	v_exp_f32_e32 v2, v2
	v_mul_f32_e32 v0, 0.5, v0
	v_add_f32_e32 v2, 1.0, v2
	v_div_scale_f32 v6, s[2:3], v2, v2, 2.0
	v_rcp_f32_e32 v7, v6
	s_nop 0
	v_fma_f32 v8, -v6, v7, 1.0
	v_fmac_f32_e32 v7, v8, v7
	v_div_scale_f32 v8, vcc, 2.0, v2, 2.0
	v_mul_f32_e32 v9, v8, v7
	v_fma_f32 v10, -v6, v9, v8
	v_fmac_f32_e32 v9, v10, v7
	v_fma_f32 v6, -v6, v9, v8
	v_div_fmas_f32 v6, v6, v7, v9
	v_div_fixup_f32 v2, v6, v2, 2.0
	v_sub_f32_e32 v2, 1.0, v2
	v_add_f32_e32 v2, 1.0, v2
	v_mul_f32_e32 v0, v0, v2
	v_bfe_u32 v2, v0, 16, 1
	v_add3_u32 v0, v0, v2, s31
	global_store_short_d16_hi v[4:5], v0, off
	v_lshlrev_b64 v[4:5], 9, v[82:83]
	v_lshl_add_u64 v[4:5], v[4:5], 0, v[50:51]
	v_lshlrev_b64 v[4:5], 1, v[4:5]
	v_lshl_add_u64 v[6:7], s[8:9], 0, v[4:5]
	s_waitcnt vmcnt(3)
	v_lshlrev_b32_e32 v0, 16, v215
	v_fmac_f32_e32 v3, v54, v0
	v_mul_f32_e32 v0, 0x3d372713, v3
	v_mul_f32_e32 v0, v3, v0
	v_fma_f32 v0, v3, v0, v3
	v_mul_f32_e32 v0, 0x3f4c422a, v0
	v_add_f32_e32 v0, v0, v0
	v_mul_f32_e32 v0, 0x3fb8aa3b, v0
	v_exp_f32_e32 v0, v0
	s_nop 0
	v_add_f32_e32 v0, 1.0, v0
	v_div_scale_f32 v2, s[2:3], v0, v0, 2.0
	v_rcp_f32_e32 v6, v2
	s_nop 0
	v_fma_f32 v7, -v2, v6, 1.0
	v_fmac_f32_e32 v6, v7, v6
	v_div_scale_f32 v7, vcc, 2.0, v0, 2.0
	v_mul_f32_e32 v8, v7, v6
	v_fma_f32 v9, -v2, v8, v7
	v_fmac_f32_e32 v8, v9, v6
	v_fma_f32 v2, -v2, v8, v7
	v_div_fmas_f32 v2, v2, v6, v8
	v_div_fixup_f32 v0, v2, v0, 2.0
	v_sub_f32_e32 v0, 1.0, v0
	v_mul_f32_e32 v2, 0.5, v3
	v_add_f32_e32 v0, 1.0, v0
	v_mul_f32_e32 v0, v2, v0
	v_bfe_u32 v2, v0, 16, 1
	v_add3_u32 v0, v0, v2, s31
	v_lshl_add_u64 v[2:3], s[28:29], 0, v[4:5]
	global_store_short_d16_hi v[2:3], v0, off
	s_barrier
	s_cbranch_scc1 .LBB0_718
